# v37 + non-temporal hints on the conv work items' streaming loads/stores inside the attention phase
# speedup vs baseline: 1.0082x; 1.0050x over previous
.Lp3_conv:
	v_readfirstlane_b32 s1, v202
	v_mov_b32_e32 v200, v164
	s_lshr_b32 s1, s1, 6
	s_lshl_b32 s52, s0, 3
	s_add_i32 s52, s52, s1
	s_lshl_b32 s20, s52, 4
	v_readlane_b32 s36, v248, 12
	v_readlane_b32 s37, v248, 13
	v_readlane_b32 s8, v249, 3
	v_readlane_b32 s9, v249, 4
	v_and_b32_e32 v2, 63, v202
	v_lshlrev_b32_e32 v3, 5, v2
	v_lshlrev_b32_e32 v2, 4, v2
	s_add_u32 s8, s8, 0x10000000
	s_addc_u32 s9, s9, 0
	s_lshl_b32 s10, s20, 11
	s_mul_i32 s11, s20, 0xc00
	s_add_u32 s12, s74, s10
	s_addc_u32 s13, s75, 0
	s_add_u32 s14, s8, s10
	s_addc_u32 s15, s9, 0
	s_add_u32 s16, s68, s11
	s_addc_u32 s17, s69, 0
	s_add_u32 s16, s16, 0x400
	s_addc_u32 s17, s17, 0
	s_and_b32 s21, s52, 0xff
	s_cmp_lg_u32 s21, 0
	s_cselect_b32 s22, 0xfffff800, 0
	s_cselect_b32 s23, -1, 0
	s_cselect_b32 s24, 0xfffff000, 0
	s_add_u32 s26, s12, s22
	s_addc_u32 s27, s13, s23
	s_add_u32 s28, s12, s24
	s_addc_u32 s29, s13, s23
	s_add_u32 s18, s36, 0x0
	s_addc_u32 s19, s37, 0
	global_load_dwordx4 v[132:135], v3, s[18:19]
	global_load_dwordx4 v[136:139], v3, s[18:19] offset:16
	s_add_u32 s18, s36, 0x1000
	s_addc_u32 s19, s37, 0
	global_load_dwordx4 v[140:143], v3, s[18:19]
	global_load_dwordx4 v[144:147], v3, s[18:19] offset:16
	s_add_u32 s18, s36, 0x2000
	s_addc_u32 s19, s37, 0
	global_load_dwordx4 v[148:151], v3, s[18:19]
	global_load_dwordx4 v[152:155], v3, s[18:19] offset:16
	s_add_u32 s18, s36, 0x800
	s_addc_u32 s19, s37, 0
	global_load_dwordx4 v[156:159], v3, s[18:19]
	global_load_dwordx4 v[160:163], v3, s[18:19] offset:16
	s_add_u32 s18, s36, 0x1800
	s_addc_u32 s19, s37, 0
	global_load_dwordx4 v[164:167], v3, s[18:19]
	global_load_dwordx4 v[168:171], v3, s[18:19] offset:16
	s_add_u32 s18, s36, 0x2800
	s_addc_u32 s19, s37, 0
	global_load_dwordx4 v[172:175], v3, s[18:19]
	global_load_dwordx4 v[176:179], v3, s[18:19] offset:16
	global_load_dwordx4 v[180:183], v2, s[26:27] nt
	global_load_dwordx4 v[184:187], v2, s[28:29] nt
	global_load_dwordx4 v[188:191], v2, s[26:27] offset:1024 nt
	global_load_dwordx4 v[196:199], v2, s[28:29] offset:1024 nt
	s_add_u32 s18, s12, 0x0
	s_addc_u32 s19, s13, 0
	s_add_u32 s30, s14, 0x0
	s_addc_u32 s31, s15, 0
	global_load_dwordx4 v[4:7], v2, s[18:19] nt
	global_load_dwordx4 v[36:39], v2, s[30:31] nt
	s_add_u32 s18, s12, 0x800
	s_addc_u32 s19, s13, 0
	s_add_u32 s30, s14, 0x800
	s_addc_u32 s31, s15, 0
	global_load_dwordx4 v[8:11], v2, s[18:19] nt
	global_load_dwordx4 v[40:43], v2, s[30:31] nt
	s_add_u32 s18, s12, 0x1000
	s_addc_u32 s19, s13, 0
	s_add_u32 s30, s14, 0x1000
	s_addc_u32 s31, s15, 0
	global_load_dwordx4 v[12:15], v2, s[18:19] nt
	global_load_dwordx4 v[44:47], v2, s[30:31] nt
	s_add_u32 s18, s12, 0x1800
	s_addc_u32 s19, s13, 0
	s_add_u32 s30, s14, 0x1800
	s_addc_u32 s31, s15, 0
	global_load_dwordx4 v[16:19], v2, s[18:19] nt
	global_load_dwordx4 v[48:51], v2, s[30:31] nt
	s_add_u32 s18, s12, 0x2000
	s_addc_u32 s19, s13, 0
	s_add_u32 s30, s14, 0x2000
	s_addc_u32 s31, s15, 0
	global_load_dwordx4 v[20:23], v2, s[18:19] nt
	global_load_dwordx4 v[52:55], v2, s[30:31] nt
	s_add_u32 s18, s12, 0x2800
	s_addc_u32 s19, s13, 0
	s_add_u32 s30, s14, 0x2800
	s_addc_u32 s31, s15, 0
	global_load_dwordx4 v[24:27], v2, s[18:19] nt
	global_load_dwordx4 v[56:59], v2, s[30:31] nt
	s_add_u32 s18, s12, 0x3000
	s_addc_u32 s19, s13, 0
	s_add_u32 s30, s14, 0x3000
	s_addc_u32 s31, s15, 0
	global_load_dwordx4 v[28:31], v2, s[18:19] nt
	global_load_dwordx4 v[60:63], v2, s[30:31] nt
	s_add_u32 s18, s12, 0x3800
	s_addc_u32 s19, s13, 0
	s_add_u32 s30, s14, 0x3800
	s_addc_u32 s31, s15, 0
	global_load_dwordx4 v[32:35], v2, s[18:19] nt
	global_load_dwordx4 v[64:67], v2, s[30:31] nt
	s_add_u32 s18, s12, 0x4000
	s_addc_u32 s19, s13, 0
	s_add_u32 s30, s14, 0x4000
	s_addc_u32 s31, s15, 0
	global_load_dwordx4 v[68:71], v2, s[18:19] nt
	global_load_dwordx4 v[100:103], v2, s[30:31] nt
	s_add_u32 s18, s12, 0x4800
	s_addc_u32 s19, s13, 0
	s_add_u32 s30, s14, 0x4800
	s_addc_u32 s31, s15, 0
	global_load_dwordx4 v[72:75], v2, s[18:19] nt
	global_load_dwordx4 v[104:107], v2, s[30:31] nt
	s_add_u32 s18, s12, 0x5000
	s_addc_u32 s19, s13, 0
	s_add_u32 s30, s14, 0x5000
	s_addc_u32 s31, s15, 0
	global_load_dwordx4 v[76:79], v2, s[18:19] nt
	global_load_dwordx4 v[108:111], v2, s[30:31] nt
	s_add_u32 s18, s12, 0x5800
	s_addc_u32 s19, s13, 0
	s_add_u32 s30, s14, 0x5800
	s_addc_u32 s31, s15, 0
	global_load_dwordx4 v[80:83], v2, s[18:19] nt
	global_load_dwordx4 v[112:115], v2, s[30:31] nt
	s_add_u32 s18, s12, 0x6000
	s_addc_u32 s19, s13, 0
	s_add_u32 s30, s14, 0x6000
	s_addc_u32 s31, s15, 0
	global_load_dwordx4 v[84:87], v2, s[18:19] nt
	global_load_dwordx4 v[116:119], v2, s[30:31] nt
	s_add_u32 s18, s12, 0x6800
	s_addc_u32 s19, s13, 0
	s_add_u32 s30, s14, 0x6800
	s_addc_u32 s31, s15, 0
	global_load_dwordx4 v[88:91], v2, s[18:19] nt
	global_load_dwordx4 v[120:123], v2, s[30:31] nt
	s_add_u32 s18, s12, 0x7000
	s_addc_u32 s19, s13, 0
	s_add_u32 s30, s14, 0x7000
	s_addc_u32 s31, s15, 0
	global_load_dwordx4 v[92:95], v2, s[18:19] nt
	global_load_dwordx4 v[124:127], v2, s[30:31] nt
	s_add_u32 s18, s12, 0x7800
	s_addc_u32 s19, s13, 0
	s_add_u32 s30, s14, 0x7800
	s_addc_u32 s31, s15, 0
	global_load_dwordx4 v[96:99], v2, s[18:19] nt
	global_load_dwordx4 v[128:131], v2, s[30:31] nt
	s_waitcnt vmcnt(16)
	s_cmp_lg_u32 s21, 0
	s_cbranch_scc1 .Lcv_nz0
	v_mov_b32_e32 v180, 0
	v_mov_b32_e32 v181, 0
	v_mov_b32_e32 v182, 0
	v_mov_b32_e32 v183, 0
	v_mov_b32_e32 v184, 0
	v_mov_b32_e32 v185, 0
	v_mov_b32_e32 v186, 0
	v_mov_b32_e32 v187, 0
.Lcv_nz0:
	v_lshlrev_b32_e32 v220, 16, v184
	v_and_b32_e32 v221, 0xffff0000, v184
	v_lshlrev_b32_e32 v222, 16, v185
	v_and_b32_e32 v223, 0xffff0000, v185
	v_lshlrev_b32_e32 v224, 16, v186
	v_and_b32_e32 v225, 0xffff0000, v186
	v_lshlrev_b32_e32 v226, 16, v187
	v_and_b32_e32 v227, 0xffff0000, v187
	v_lshlrev_b32_e32 v228, 16, v180
	v_and_b32_e32 v229, 0xffff0000, v180
	v_lshlrev_b32_e32 v230, 16, v181
	v_and_b32_e32 v231, 0xffff0000, v181
	v_lshlrev_b32_e32 v232, 16, v182
	v_and_b32_e32 v233, 0xffff0000, v182
	v_lshlrev_b32_e32 v234, 16, v183
	v_and_b32_e32 v235, 0xffff0000, v183
	v_lshlrev_b32_e32 v204, 16, v4
	v_and_b32_e32 v205, 0xffff0000, v4
	v_lshlrev_b32_e32 v206, 16, v5
	v_and_b32_e32 v207, 0xffff0000, v5
	v_lshlrev_b32_e32 v208, 16, v6
	v_and_b32_e32 v209, 0xffff0000, v6
	v_lshlrev_b32_e32 v210, 16, v7
	v_and_b32_e32 v211, 0xffff0000, v7
	v_lshlrev_b32_e32 v236, 16, v36
	v_and_b32_e32 v237, 0xffff0000, v36
	v_lshlrev_b32_e32 v238, 16, v37
	v_and_b32_e32 v239, 0xffff0000, v37
	v_lshlrev_b32_e32 v240, 16, v38
	v_and_b32_e32 v241, 0xffff0000, v38
	v_lshlrev_b32_e32 v242, 16, v39
	v_and_b32_e32 v243, 0xffff0000, v39
	v_pk_mul_f32 v[244:245], v[140:141], v[228:229]
	v_pk_fma_f32 v[244:245], v[132:133], v[220:221], v[244:245]
	v_pk_fma_f32 v[244:245], v[148:149], v[204:205], v[244:245]
	v_pk_mul_f32 v[244:245], v[244:245], v[236:237]
	v_cvt_pk_bf16_f32 v212, v244, v245
	v_pk_mul_f32 v[246:247], v[142:143], v[230:231]
	v_pk_fma_f32 v[246:247], v[134:135], v[222:223], v[246:247]
	v_pk_fma_f32 v[246:247], v[150:151], v[206:207], v[246:247]
	v_pk_mul_f32 v[246:247], v[246:247], v[238:239]
	v_cvt_pk_bf16_f32 v213, v246, v247
	v_pk_mul_f32 v[244:245], v[144:145], v[232:233]
	v_pk_fma_f32 v[244:245], v[136:137], v[224:225], v[244:245]
	v_pk_fma_f32 v[244:245], v[152:153], v[208:209], v[244:245]
	v_pk_mul_f32 v[244:245], v[244:245], v[240:241]
	v_cvt_pk_bf16_f32 v214, v244, v245
	v_pk_mul_f32 v[246:247], v[146:147], v[234:235]
	v_pk_fma_f32 v[246:247], v[138:139], v[226:227], v[246:247]
	v_pk_fma_f32 v[246:247], v[154:155], v[210:211], v[246:247]
	v_pk_mul_f32 v[246:247], v[246:247], v[242:243]
	v_cvt_pk_bf16_f32 v215, v246, v247
	s_add_u32 s18, s16, 0x0
	s_addc_u32 s19, s17, 0
	global_store_dwordx4 v2, v[212:215], s[18:19] nt
	v_lshlrev_b32_e32 v220, 16, v8
	v_and_b32_e32 v221, 0xffff0000, v8
	v_lshlrev_b32_e32 v222, 16, v9
	v_and_b32_e32 v223, 0xffff0000, v9
	v_lshlrev_b32_e32 v224, 16, v10
	v_and_b32_e32 v225, 0xffff0000, v10
	v_lshlrev_b32_e32 v226, 16, v11
	v_and_b32_e32 v227, 0xffff0000, v11
	v_lshlrev_b32_e32 v236, 16, v40
	v_and_b32_e32 v237, 0xffff0000, v40
	v_lshlrev_b32_e32 v238, 16, v41
	v_and_b32_e32 v239, 0xffff0000, v41
	v_lshlrev_b32_e32 v240, 16, v42
	v_and_b32_e32 v241, 0xffff0000, v42
	v_lshlrev_b32_e32 v242, 16, v43
	v_and_b32_e32 v243, 0xffff0000, v43
	v_pk_mul_f32 v[244:245], v[140:141], v[204:205]
	v_pk_fma_f32 v[244:245], v[132:133], v[228:229], v[244:245]
	v_pk_fma_f32 v[244:245], v[148:149], v[220:221], v[244:245]
	v_pk_mul_f32 v[244:245], v[244:245], v[236:237]
	v_cvt_pk_bf16_f32 v216, v244, v245
	v_pk_mul_f32 v[246:247], v[142:143], v[206:207]
	v_pk_fma_f32 v[246:247], v[134:135], v[230:231], v[246:247]
	v_pk_fma_f32 v[246:247], v[150:151], v[222:223], v[246:247]
	v_pk_mul_f32 v[246:247], v[246:247], v[238:239]
	v_cvt_pk_bf16_f32 v217, v246, v247
	v_pk_mul_f32 v[244:245], v[144:145], v[208:209]
	v_pk_fma_f32 v[244:245], v[136:137], v[232:233], v[244:245]
	v_pk_fma_f32 v[244:245], v[152:153], v[224:225], v[244:245]
	v_pk_mul_f32 v[244:245], v[244:245], v[240:241]
	v_cvt_pk_bf16_f32 v218, v244, v245
	v_pk_mul_f32 v[246:247], v[146:147], v[210:211]
	v_pk_fma_f32 v[246:247], v[138:139], v[234:235], v[246:247]
	v_pk_fma_f32 v[246:247], v[154:155], v[226:227], v[246:247]
	v_pk_mul_f32 v[246:247], v[246:247], v[242:243]
	v_cvt_pk_bf16_f32 v219, v246, v247
	s_add_u32 s18, s16, 0xc00
	s_addc_u32 s19, s17, 0
	global_store_dwordx4 v2, v[216:219], s[18:19] nt
	v_lshlrev_b32_e32 v228, 16, v12
	v_and_b32_e32 v229, 0xffff0000, v12
	v_lshlrev_b32_e32 v230, 16, v13
	v_and_b32_e32 v231, 0xffff0000, v13
	v_lshlrev_b32_e32 v232, 16, v14
	v_and_b32_e32 v233, 0xffff0000, v14
	v_lshlrev_b32_e32 v234, 16, v15
	v_and_b32_e32 v235, 0xffff0000, v15
	v_lshlrev_b32_e32 v236, 16, v44
	v_and_b32_e32 v237, 0xffff0000, v44
	v_lshlrev_b32_e32 v238, 16, v45
	v_and_b32_e32 v239, 0xffff0000, v45
	v_lshlrev_b32_e32 v240, 16, v46
	v_and_b32_e32 v241, 0xffff0000, v46
	v_lshlrev_b32_e32 v242, 16, v47
	v_and_b32_e32 v243, 0xffff0000, v47
	v_pk_mul_f32 v[244:245], v[140:141], v[220:221]
	v_pk_fma_f32 v[244:245], v[132:133], v[204:205], v[244:245]
	v_pk_fma_f32 v[244:245], v[148:149], v[228:229], v[244:245]
	v_pk_mul_f32 v[244:245], v[244:245], v[236:237]
	v_cvt_pk_bf16_f32 v212, v244, v245
	v_pk_mul_f32 v[246:247], v[142:143], v[222:223]
	v_pk_fma_f32 v[246:247], v[134:135], v[206:207], v[246:247]
	v_pk_fma_f32 v[246:247], v[150:151], v[230:231], v[246:247]
	v_pk_mul_f32 v[246:247], v[246:247], v[238:239]
	v_cvt_pk_bf16_f32 v213, v246, v247
	v_pk_mul_f32 v[244:245], v[144:145], v[224:225]
	v_pk_fma_f32 v[244:245], v[136:137], v[208:209], v[244:245]
	v_pk_fma_f32 v[244:245], v[152:153], v[232:233], v[244:245]
	v_pk_mul_f32 v[244:245], v[244:245], v[240:241]
	v_cvt_pk_bf16_f32 v214, v244, v245
	v_pk_mul_f32 v[246:247], v[146:147], v[226:227]
	v_pk_fma_f32 v[246:247], v[138:139], v[210:211], v[246:247]
	v_pk_fma_f32 v[246:247], v[154:155], v[234:235], v[246:247]
	v_pk_mul_f32 v[246:247], v[246:247], v[242:243]
	v_cvt_pk_bf16_f32 v215, v246, v247
	s_add_u32 s18, s16, 0x1800
	s_addc_u32 s19, s17, 0
	global_store_dwordx4 v2, v[212:215], s[18:19] nt
	v_lshlrev_b32_e32 v204, 16, v16
	v_and_b32_e32 v205, 0xffff0000, v16
	v_lshlrev_b32_e32 v206, 16, v17
	v_and_b32_e32 v207, 0xffff0000, v17
	v_lshlrev_b32_e32 v208, 16, v18
	v_and_b32_e32 v209, 0xffff0000, v18
	v_lshlrev_b32_e32 v210, 16, v19
	v_and_b32_e32 v211, 0xffff0000, v19
	v_lshlrev_b32_e32 v236, 16, v48
	v_and_b32_e32 v237, 0xffff0000, v48
	v_lshlrev_b32_e32 v238, 16, v49
	v_and_b32_e32 v239, 0xffff0000, v49
	v_lshlrev_b32_e32 v240, 16, v50
	v_and_b32_e32 v241, 0xffff0000, v50
	v_lshlrev_b32_e32 v242, 16, v51
	v_and_b32_e32 v243, 0xffff0000, v51
	v_pk_mul_f32 v[244:245], v[140:141], v[228:229]
	v_pk_fma_f32 v[244:245], v[132:133], v[220:221], v[244:245]
	v_pk_fma_f32 v[244:245], v[148:149], v[204:205], v[244:245]
	v_pk_mul_f32 v[244:245], v[244:245], v[236:237]
	v_cvt_pk_bf16_f32 v216, v244, v245
	v_pk_mul_f32 v[246:247], v[142:143], v[230:231]
	v_pk_fma_f32 v[246:247], v[134:135], v[222:223], v[246:247]
	v_pk_fma_f32 v[246:247], v[150:151], v[206:207], v[246:247]
	v_pk_mul_f32 v[246:247], v[246:247], v[238:239]
	v_cvt_pk_bf16_f32 v217, v246, v247
	v_pk_mul_f32 v[244:245], v[144:145], v[232:233]
	v_pk_fma_f32 v[244:245], v[136:137], v[224:225], v[244:245]
	v_pk_fma_f32 v[244:245], v[152:153], v[208:209], v[244:245]
	v_pk_mul_f32 v[244:245], v[244:245], v[240:241]
	v_cvt_pk_bf16_f32 v218, v244, v245
	v_pk_mul_f32 v[246:247], v[146:147], v[234:235]
	v_pk_fma_f32 v[246:247], v[138:139], v[226:227], v[246:247]
	v_pk_fma_f32 v[246:247], v[154:155], v[210:211], v[246:247]
	v_pk_mul_f32 v[246:247], v[246:247], v[242:243]
	v_cvt_pk_bf16_f32 v219, v246, v247
	s_add_u32 s18, s16, 0x2400
	s_addc_u32 s19, s17, 0
	global_store_dwordx4 v2, v[216:219], s[18:19] nt
	v_lshlrev_b32_e32 v220, 16, v20
	v_and_b32_e32 v221, 0xffff0000, v20
	v_lshlrev_b32_e32 v222, 16, v21
	v_and_b32_e32 v223, 0xffff0000, v21
	v_lshlrev_b32_e32 v224, 16, v22
	v_and_b32_e32 v225, 0xffff0000, v22
	v_lshlrev_b32_e32 v226, 16, v23
	v_and_b32_e32 v227, 0xffff0000, v23
	v_lshlrev_b32_e32 v236, 16, v52
	v_and_b32_e32 v237, 0xffff0000, v52
	v_lshlrev_b32_e32 v238, 16, v53
	v_and_b32_e32 v239, 0xffff0000, v53
	v_lshlrev_b32_e32 v240, 16, v54
	v_and_b32_e32 v241, 0xffff0000, v54
	v_lshlrev_b32_e32 v242, 16, v55
	v_and_b32_e32 v243, 0xffff0000, v55
	v_pk_mul_f32 v[244:245], v[140:141], v[204:205]
	v_pk_fma_f32 v[244:245], v[132:133], v[228:229], v[244:245]
	v_pk_fma_f32 v[244:245], v[148:149], v[220:221], v[244:245]
	v_pk_mul_f32 v[244:245], v[244:245], v[236:237]
	v_cvt_pk_bf16_f32 v212, v244, v245
	v_pk_mul_f32 v[246:247], v[142:143], v[206:207]
	v_pk_fma_f32 v[246:247], v[134:135], v[230:231], v[246:247]
	v_pk_fma_f32 v[246:247], v[150:151], v[222:223], v[246:247]
	v_pk_mul_f32 v[246:247], v[246:247], v[238:239]
	v_cvt_pk_bf16_f32 v213, v246, v247
	v_pk_mul_f32 v[244:245], v[144:145], v[208:209]
	v_pk_fma_f32 v[244:245], v[136:137], v[232:233], v[244:245]
	v_pk_fma_f32 v[244:245], v[152:153], v[224:225], v[244:245]
	v_pk_mul_f32 v[244:245], v[244:245], v[240:241]
	v_cvt_pk_bf16_f32 v214, v244, v245
	v_pk_mul_f32 v[246:247], v[146:147], v[210:211]
	v_pk_fma_f32 v[246:247], v[138:139], v[234:235], v[246:247]
	v_pk_fma_f32 v[246:247], v[154:155], v[226:227], v[246:247]
	v_pk_mul_f32 v[246:247], v[246:247], v[242:243]
	v_cvt_pk_bf16_f32 v215, v246, v247
	s_add_u32 s18, s16, 0x3000
	s_addc_u32 s19, s17, 0
	global_store_dwordx4 v2, v[212:215], s[18:19] nt
	v_lshlrev_b32_e32 v228, 16, v24
	v_and_b32_e32 v229, 0xffff0000, v24
	v_lshlrev_b32_e32 v230, 16, v25
	v_and_b32_e32 v231, 0xffff0000, v25
	v_lshlrev_b32_e32 v232, 16, v26
	v_and_b32_e32 v233, 0xffff0000, v26
	v_lshlrev_b32_e32 v234, 16, v27
	v_and_b32_e32 v235, 0xffff0000, v27
	v_lshlrev_b32_e32 v236, 16, v56
	v_and_b32_e32 v237, 0xffff0000, v56
	v_lshlrev_b32_e32 v238, 16, v57
	v_and_b32_e32 v239, 0xffff0000, v57
	v_lshlrev_b32_e32 v240, 16, v58
	v_and_b32_e32 v241, 0xffff0000, v58
	v_lshlrev_b32_e32 v242, 16, v59
	v_and_b32_e32 v243, 0xffff0000, v59
	v_pk_mul_f32 v[244:245], v[140:141], v[220:221]
	v_pk_fma_f32 v[244:245], v[132:133], v[204:205], v[244:245]
	v_pk_fma_f32 v[244:245], v[148:149], v[228:229], v[244:245]
	v_pk_mul_f32 v[244:245], v[244:245], v[236:237]
	v_cvt_pk_bf16_f32 v216, v244, v245
	v_pk_mul_f32 v[246:247], v[142:143], v[222:223]
	v_pk_fma_f32 v[246:247], v[134:135], v[206:207], v[246:247]
	v_pk_fma_f32 v[246:247], v[150:151], v[230:231], v[246:247]
	v_pk_mul_f32 v[246:247], v[246:247], v[238:239]
	v_cvt_pk_bf16_f32 v217, v246, v247
	v_pk_mul_f32 v[244:245], v[144:145], v[224:225]
	v_pk_fma_f32 v[244:245], v[136:137], v[208:209], v[244:245]
	v_pk_fma_f32 v[244:245], v[152:153], v[232:233], v[244:245]
	v_pk_mul_f32 v[244:245], v[244:245], v[240:241]
	v_cvt_pk_bf16_f32 v218, v244, v245
	v_pk_mul_f32 v[246:247], v[146:147], v[226:227]
	v_pk_fma_f32 v[246:247], v[138:139], v[210:211], v[246:247]
	v_pk_fma_f32 v[246:247], v[154:155], v[234:235], v[246:247]
	v_pk_mul_f32 v[246:247], v[246:247], v[242:243]
	v_cvt_pk_bf16_f32 v219, v246, v247
	s_add_u32 s18, s16, 0x3c00
	s_addc_u32 s19, s17, 0
	global_store_dwordx4 v2, v[216:219], s[18:19] nt
	v_lshlrev_b32_e32 v204, 16, v28
	v_and_b32_e32 v205, 0xffff0000, v28
	v_lshlrev_b32_e32 v206, 16, v29
	v_and_b32_e32 v207, 0xffff0000, v29
	v_lshlrev_b32_e32 v208, 16, v30
	v_and_b32_e32 v209, 0xffff0000, v30
	v_lshlrev_b32_e32 v210, 16, v31
	v_and_b32_e32 v211, 0xffff0000, v31
	v_lshlrev_b32_e32 v236, 16, v60
	v_and_b32_e32 v237, 0xffff0000, v60
	v_lshlrev_b32_e32 v238, 16, v61
	v_and_b32_e32 v239, 0xffff0000, v61
	v_lshlrev_b32_e32 v240, 16, v62
	v_and_b32_e32 v241, 0xffff0000, v62
	v_lshlrev_b32_e32 v242, 16, v63
	v_and_b32_e32 v243, 0xffff0000, v63
	v_pk_mul_f32 v[244:245], v[140:141], v[228:229]
	v_pk_fma_f32 v[244:245], v[132:133], v[220:221], v[244:245]
	v_pk_fma_f32 v[244:245], v[148:149], v[204:205], v[244:245]
	v_pk_mul_f32 v[244:245], v[244:245], v[236:237]
	v_cvt_pk_bf16_f32 v212, v244, v245
	v_pk_mul_f32 v[246:247], v[142:143], v[230:231]
	v_pk_fma_f32 v[246:247], v[134:135], v[222:223], v[246:247]
	v_pk_fma_f32 v[246:247], v[150:151], v[206:207], v[246:247]
	v_pk_mul_f32 v[246:247], v[246:247], v[238:239]
	v_cvt_pk_bf16_f32 v213, v246, v247
	v_pk_mul_f32 v[244:245], v[144:145], v[232:233]
	v_pk_fma_f32 v[244:245], v[136:137], v[224:225], v[244:245]
	v_pk_fma_f32 v[244:245], v[152:153], v[208:209], v[244:245]
	v_pk_mul_f32 v[244:245], v[244:245], v[240:241]
	v_cvt_pk_bf16_f32 v214, v244, v245
	v_pk_mul_f32 v[246:247], v[146:147], v[234:235]
	v_pk_fma_f32 v[246:247], v[138:139], v[226:227], v[246:247]
	v_pk_fma_f32 v[246:247], v[154:155], v[210:211], v[246:247]
	v_pk_mul_f32 v[246:247], v[246:247], v[242:243]
	v_cvt_pk_bf16_f32 v215, v246, v247
	s_add_u32 s18, s16, 0x4800
	s_addc_u32 s19, s17, 0
	global_store_dwordx4 v2, v[212:215], s[18:19] nt
	v_lshlrev_b32_e32 v220, 16, v32
	v_and_b32_e32 v221, 0xffff0000, v32
	v_lshlrev_b32_e32 v222, 16, v33
	v_and_b32_e32 v223, 0xffff0000, v33
	v_lshlrev_b32_e32 v224, 16, v34
	v_and_b32_e32 v225, 0xffff0000, v34
	v_lshlrev_b32_e32 v226, 16, v35
	v_and_b32_e32 v227, 0xffff0000, v35
	v_lshlrev_b32_e32 v236, 16, v64
	v_and_b32_e32 v237, 0xffff0000, v64
	v_lshlrev_b32_e32 v238, 16, v65
	v_and_b32_e32 v239, 0xffff0000, v65
	v_lshlrev_b32_e32 v240, 16, v66
	v_and_b32_e32 v241, 0xffff0000, v66
	v_lshlrev_b32_e32 v242, 16, v67
	v_and_b32_e32 v243, 0xffff0000, v67
	v_pk_mul_f32 v[244:245], v[140:141], v[204:205]
	v_pk_fma_f32 v[244:245], v[132:133], v[228:229], v[244:245]
	v_pk_fma_f32 v[244:245], v[148:149], v[220:221], v[244:245]
	v_pk_mul_f32 v[244:245], v[244:245], v[236:237]
	v_cvt_pk_bf16_f32 v216, v244, v245
	v_pk_mul_f32 v[246:247], v[142:143], v[206:207]
	v_pk_fma_f32 v[246:247], v[134:135], v[230:231], v[246:247]
	v_pk_fma_f32 v[246:247], v[150:151], v[222:223], v[246:247]
	v_pk_mul_f32 v[246:247], v[246:247], v[238:239]
	v_cvt_pk_bf16_f32 v217, v246, v247
	v_pk_mul_f32 v[244:245], v[144:145], v[208:209]
	v_pk_fma_f32 v[244:245], v[136:137], v[232:233], v[244:245]
	v_pk_fma_f32 v[244:245], v[152:153], v[224:225], v[244:245]
	v_pk_mul_f32 v[244:245], v[244:245], v[240:241]
	v_cvt_pk_bf16_f32 v218, v244, v245
	v_pk_mul_f32 v[246:247], v[146:147], v[210:211]
	v_pk_fma_f32 v[246:247], v[138:139], v[234:235], v[246:247]
	v_pk_fma_f32 v[246:247], v[154:155], v[226:227], v[246:247]
	v_pk_mul_f32 v[246:247], v[246:247], v[242:243]
	v_cvt_pk_bf16_f32 v219, v246, v247
	s_add_u32 s18, s16, 0x5400
	s_addc_u32 s19, s17, 0
	global_store_dwordx4 v2, v[216:219], s[18:19] nt
	s_add_u32 s18, s12, 0x400
	s_addc_u32 s19, s13, 0
	s_add_u32 s30, s14, 0x400
	s_addc_u32 s31, s15, 0
	global_load_dwordx4 v[4:7], v2, s[18:19] nt
	global_load_dwordx4 v[36:39], v2, s[30:31] nt
	s_add_u32 s18, s12, 0xc00
	s_addc_u32 s19, s13, 0
	s_add_u32 s30, s14, 0xc00
	s_addc_u32 s31, s15, 0
	global_load_dwordx4 v[8:11], v2, s[18:19] nt
	global_load_dwordx4 v[40:43], v2, s[30:31] nt
	s_add_u32 s18, s12, 0x1400
	s_addc_u32 s19, s13, 0
	s_add_u32 s30, s14, 0x1400
	s_addc_u32 s31, s15, 0
	global_load_dwordx4 v[12:15], v2, s[18:19] nt
	global_load_dwordx4 v[44:47], v2, s[30:31] nt
	s_add_u32 s18, s12, 0x1c00
	s_addc_u32 s19, s13, 0
	s_add_u32 s30, s14, 0x1c00
	s_addc_u32 s31, s15, 0
	global_load_dwordx4 v[16:19], v2, s[18:19] nt
	global_load_dwordx4 v[48:51], v2, s[30:31] nt
	s_add_u32 s18, s12, 0x2400
	s_addc_u32 s19, s13, 0
	s_add_u32 s30, s14, 0x2400
	s_addc_u32 s31, s15, 0
	global_load_dwordx4 v[20:23], v2, s[18:19] nt
	global_load_dwordx4 v[52:55], v2, s[30:31] nt
	s_add_u32 s18, s12, 0x2c00
	s_addc_u32 s19, s13, 0
	s_add_u32 s30, s14, 0x2c00
	s_addc_u32 s31, s15, 0
	global_load_dwordx4 v[24:27], v2, s[18:19] nt
	global_load_dwordx4 v[56:59], v2, s[30:31] nt
	s_add_u32 s18, s12, 0x3400
	s_addc_u32 s19, s13, 0
	s_add_u32 s30, s14, 0x3400
	s_addc_u32 s31, s15, 0
	global_load_dwordx4 v[28:31], v2, s[18:19] nt
	global_load_dwordx4 v[60:63], v2, s[30:31] nt
	s_add_u32 s18, s12, 0x3c00
	s_addc_u32 s19, s13, 0
	s_add_u32 s30, s14, 0x3c00
	s_addc_u32 s31, s15, 0
	global_load_dwordx4 v[32:35], v2, s[18:19] nt
	global_load_dwordx4 v[64:67], v2, s[30:31] nt
	s_waitcnt vmcnt(24)
	v_lshlrev_b32_e32 v228, 16, v68
	v_and_b32_e32 v229, 0xffff0000, v68
	v_lshlrev_b32_e32 v230, 16, v69
	v_and_b32_e32 v231, 0xffff0000, v69
	v_lshlrev_b32_e32 v232, 16, v70
	v_and_b32_e32 v233, 0xffff0000, v70
	v_lshlrev_b32_e32 v234, 16, v71
	v_and_b32_e32 v235, 0xffff0000, v71
	v_lshlrev_b32_e32 v236, 16, v100
	v_and_b32_e32 v237, 0xffff0000, v100
	v_lshlrev_b32_e32 v238, 16, v101
	v_and_b32_e32 v239, 0xffff0000, v101
	v_lshlrev_b32_e32 v240, 16, v102
	v_and_b32_e32 v241, 0xffff0000, v102
	v_lshlrev_b32_e32 v242, 16, v103
	v_and_b32_e32 v243, 0xffff0000, v103
	v_pk_mul_f32 v[244:245], v[140:141], v[220:221]
	v_pk_fma_f32 v[244:245], v[132:133], v[204:205], v[244:245]
	v_pk_fma_f32 v[244:245], v[148:149], v[228:229], v[244:245]
	v_pk_mul_f32 v[244:245], v[244:245], v[236:237]
	v_cvt_pk_bf16_f32 v212, v244, v245
	v_pk_mul_f32 v[246:247], v[142:143], v[222:223]
	v_pk_fma_f32 v[246:247], v[134:135], v[206:207], v[246:247]
	v_pk_fma_f32 v[246:247], v[150:151], v[230:231], v[246:247]
	v_pk_mul_f32 v[246:247], v[246:247], v[238:239]
	v_cvt_pk_bf16_f32 v213, v246, v247
	v_pk_mul_f32 v[244:245], v[144:145], v[224:225]
	v_pk_fma_f32 v[244:245], v[136:137], v[208:209], v[244:245]
	v_pk_fma_f32 v[244:245], v[152:153], v[232:233], v[244:245]
	v_pk_mul_f32 v[244:245], v[244:245], v[240:241]
	v_cvt_pk_bf16_f32 v214, v244, v245
	v_pk_mul_f32 v[246:247], v[146:147], v[226:227]
	v_pk_fma_f32 v[246:247], v[138:139], v[210:211], v[246:247]
	v_pk_fma_f32 v[246:247], v[154:155], v[234:235], v[246:247]
	v_pk_mul_f32 v[246:247], v[246:247], v[242:243]
	v_cvt_pk_bf16_f32 v215, v246, v247
	s_add_u32 s18, s16, 0x6000
	s_addc_u32 s19, s17, 0
	global_store_dwordx4 v2, v[212:215], s[18:19] nt
	v_lshlrev_b32_e32 v204, 16, v72
	v_and_b32_e32 v205, 0xffff0000, v72
	v_lshlrev_b32_e32 v206, 16, v73
	v_and_b32_e32 v207, 0xffff0000, v73
	v_lshlrev_b32_e32 v208, 16, v74
	v_and_b32_e32 v209, 0xffff0000, v74
	v_lshlrev_b32_e32 v210, 16, v75
	v_and_b32_e32 v211, 0xffff0000, v75
	v_lshlrev_b32_e32 v236, 16, v104
	v_and_b32_e32 v237, 0xffff0000, v104
	v_lshlrev_b32_e32 v238, 16, v105
	v_and_b32_e32 v239, 0xffff0000, v105
	v_lshlrev_b32_e32 v240, 16, v106
	v_and_b32_e32 v241, 0xffff0000, v106
	v_lshlrev_b32_e32 v242, 16, v107
	v_and_b32_e32 v243, 0xffff0000, v107
	v_pk_mul_f32 v[244:245], v[140:141], v[228:229]
	v_pk_fma_f32 v[244:245], v[132:133], v[220:221], v[244:245]
	v_pk_fma_f32 v[244:245], v[148:149], v[204:205], v[244:245]
	v_pk_mul_f32 v[244:245], v[244:245], v[236:237]
	v_cvt_pk_bf16_f32 v216, v244, v245
	v_pk_mul_f32 v[246:247], v[142:143], v[230:231]
	v_pk_fma_f32 v[246:247], v[134:135], v[222:223], v[246:247]
	v_pk_fma_f32 v[246:247], v[150:151], v[206:207], v[246:247]
	v_pk_mul_f32 v[246:247], v[246:247], v[238:239]
	v_cvt_pk_bf16_f32 v217, v246, v247
	v_pk_mul_f32 v[244:245], v[144:145], v[232:233]
	v_pk_fma_f32 v[244:245], v[136:137], v[224:225], v[244:245]
	v_pk_fma_f32 v[244:245], v[152:153], v[208:209], v[244:245]
	v_pk_mul_f32 v[244:245], v[244:245], v[240:241]
	v_cvt_pk_bf16_f32 v218, v244, v245
	v_pk_mul_f32 v[246:247], v[146:147], v[234:235]
	v_pk_fma_f32 v[246:247], v[138:139], v[226:227], v[246:247]
	v_pk_fma_f32 v[246:247], v[154:155], v[210:211], v[246:247]
	v_pk_mul_f32 v[246:247], v[246:247], v[242:243]
	v_cvt_pk_bf16_f32 v219, v246, v247
	s_add_u32 s18, s16, 0x6c00
	s_addc_u32 s19, s17, 0
	global_store_dwordx4 v2, v[216:219], s[18:19] nt
	v_lshlrev_b32_e32 v220, 16, v76
	v_and_b32_e32 v221, 0xffff0000, v76
	v_lshlrev_b32_e32 v222, 16, v77
	v_and_b32_e32 v223, 0xffff0000, v77
	v_lshlrev_b32_e32 v224, 16, v78
	v_and_b32_e32 v225, 0xffff0000, v78
	v_lshlrev_b32_e32 v226, 16, v79
	v_and_b32_e32 v227, 0xffff0000, v79
	v_lshlrev_b32_e32 v236, 16, v108
	v_and_b32_e32 v237, 0xffff0000, v108
	v_lshlrev_b32_e32 v238, 16, v109
	v_and_b32_e32 v239, 0xffff0000, v109
	v_lshlrev_b32_e32 v240, 16, v110
	v_and_b32_e32 v241, 0xffff0000, v110
	v_lshlrev_b32_e32 v242, 16, v111
	v_and_b32_e32 v243, 0xffff0000, v111
	v_pk_mul_f32 v[244:245], v[140:141], v[204:205]
	v_pk_fma_f32 v[244:245], v[132:133], v[228:229], v[244:245]
	v_pk_fma_f32 v[244:245], v[148:149], v[220:221], v[244:245]
	v_pk_mul_f32 v[244:245], v[244:245], v[236:237]
	v_cvt_pk_bf16_f32 v212, v244, v245
	v_pk_mul_f32 v[246:247], v[142:143], v[206:207]
	v_pk_fma_f32 v[246:247], v[134:135], v[230:231], v[246:247]
	v_pk_fma_f32 v[246:247], v[150:151], v[222:223], v[246:247]
	v_pk_mul_f32 v[246:247], v[246:247], v[238:239]
	v_cvt_pk_bf16_f32 v213, v246, v247
	v_pk_mul_f32 v[244:245], v[144:145], v[208:209]
	v_pk_fma_f32 v[244:245], v[136:137], v[232:233], v[244:245]
	v_pk_fma_f32 v[244:245], v[152:153], v[224:225], v[244:245]
	v_pk_mul_f32 v[244:245], v[244:245], v[240:241]
	v_cvt_pk_bf16_f32 v214, v244, v245
	v_pk_mul_f32 v[246:247], v[146:147], v[210:211]
	v_pk_fma_f32 v[246:247], v[138:139], v[234:235], v[246:247]
	v_pk_fma_f32 v[246:247], v[154:155], v[226:227], v[246:247]
	v_pk_mul_f32 v[246:247], v[246:247], v[242:243]
	v_cvt_pk_bf16_f32 v215, v246, v247
	s_add_u32 s18, s16, 0x7800
	s_addc_u32 s19, s17, 0
	global_store_dwordx4 v2, v[212:215], s[18:19] nt
	v_lshlrev_b32_e32 v228, 16, v80
	v_and_b32_e32 v229, 0xffff0000, v80
	v_lshlrev_b32_e32 v230, 16, v81
	v_and_b32_e32 v231, 0xffff0000, v81
	v_lshlrev_b32_e32 v232, 16, v82
	v_and_b32_e32 v233, 0xffff0000, v82
	v_lshlrev_b32_e32 v234, 16, v83
	v_and_b32_e32 v235, 0xffff0000, v83
	v_lshlrev_b32_e32 v236, 16, v112
	v_and_b32_e32 v237, 0xffff0000, v112
	v_lshlrev_b32_e32 v238, 16, v113
	v_and_b32_e32 v239, 0xffff0000, v113
	v_lshlrev_b32_e32 v240, 16, v114
	v_and_b32_e32 v241, 0xffff0000, v114
	v_lshlrev_b32_e32 v242, 16, v115
	v_and_b32_e32 v243, 0xffff0000, v115
	v_pk_mul_f32 v[244:245], v[140:141], v[220:221]
	v_pk_fma_f32 v[244:245], v[132:133], v[204:205], v[244:245]
	v_pk_fma_f32 v[244:245], v[148:149], v[228:229], v[244:245]
	v_pk_mul_f32 v[244:245], v[244:245], v[236:237]
	v_cvt_pk_bf16_f32 v216, v244, v245
	v_pk_mul_f32 v[246:247], v[142:143], v[222:223]
	v_pk_fma_f32 v[246:247], v[134:135], v[206:207], v[246:247]
	v_pk_fma_f32 v[246:247], v[150:151], v[230:231], v[246:247]
	v_pk_mul_f32 v[246:247], v[246:247], v[238:239]
	v_cvt_pk_bf16_f32 v217, v246, v247
	v_pk_mul_f32 v[244:245], v[144:145], v[224:225]
	v_pk_fma_f32 v[244:245], v[136:137], v[208:209], v[244:245]
	v_pk_fma_f32 v[244:245], v[152:153], v[232:233], v[244:245]
	v_pk_mul_f32 v[244:245], v[244:245], v[240:241]
	v_cvt_pk_bf16_f32 v218, v244, v245
	v_pk_mul_f32 v[246:247], v[146:147], v[226:227]
	v_pk_fma_f32 v[246:247], v[138:139], v[210:211], v[246:247]
	v_pk_fma_f32 v[246:247], v[154:155], v[234:235], v[246:247]
	v_pk_mul_f32 v[246:247], v[246:247], v[242:243]
	v_cvt_pk_bf16_f32 v219, v246, v247
	s_add_u32 s18, s16, 0x8400
	s_addc_u32 s19, s17, 0
	global_store_dwordx4 v2, v[216:219], s[18:19] nt
	v_lshlrev_b32_e32 v204, 16, v84
	v_and_b32_e32 v205, 0xffff0000, v84
	v_lshlrev_b32_e32 v206, 16, v85
	v_and_b32_e32 v207, 0xffff0000, v85
	v_lshlrev_b32_e32 v208, 16, v86
	v_and_b32_e32 v209, 0xffff0000, v86
	v_lshlrev_b32_e32 v210, 16, v87
	v_and_b32_e32 v211, 0xffff0000, v87
	v_lshlrev_b32_e32 v236, 16, v116
	v_and_b32_e32 v237, 0xffff0000, v116
	v_lshlrev_b32_e32 v238, 16, v117
	v_and_b32_e32 v239, 0xffff0000, v117
	v_lshlrev_b32_e32 v240, 16, v118
	v_and_b32_e32 v241, 0xffff0000, v118
	v_lshlrev_b32_e32 v242, 16, v119
	v_and_b32_e32 v243, 0xffff0000, v119
	v_pk_mul_f32 v[244:245], v[140:141], v[228:229]
	v_pk_fma_f32 v[244:245], v[132:133], v[220:221], v[244:245]
	v_pk_fma_f32 v[244:245], v[148:149], v[204:205], v[244:245]
	v_pk_mul_f32 v[244:245], v[244:245], v[236:237]
	v_cvt_pk_bf16_f32 v212, v244, v245
	v_pk_mul_f32 v[246:247], v[142:143], v[230:231]
	v_pk_fma_f32 v[246:247], v[134:135], v[222:223], v[246:247]
	v_pk_fma_f32 v[246:247], v[150:151], v[206:207], v[246:247]
	v_pk_mul_f32 v[246:247], v[246:247], v[238:239]
	v_cvt_pk_bf16_f32 v213, v246, v247
	v_pk_mul_f32 v[244:245], v[144:145], v[232:233]
	v_pk_fma_f32 v[244:245], v[136:137], v[224:225], v[244:245]
	v_pk_fma_f32 v[244:245], v[152:153], v[208:209], v[244:245]
	v_pk_mul_f32 v[244:245], v[244:245], v[240:241]
	v_cvt_pk_bf16_f32 v214, v244, v245
	v_pk_mul_f32 v[246:247], v[146:147], v[234:235]
	v_pk_fma_f32 v[246:247], v[138:139], v[226:227], v[246:247]
	v_pk_fma_f32 v[246:247], v[154:155], v[210:211], v[246:247]
	v_pk_mul_f32 v[246:247], v[246:247], v[242:243]
	v_cvt_pk_bf16_f32 v215, v246, v247
	s_add_u32 s18, s16, 0x9000
	s_addc_u32 s19, s17, 0
	global_store_dwordx4 v2, v[212:215], s[18:19] nt
	v_lshlrev_b32_e32 v220, 16, v88
	v_and_b32_e32 v221, 0xffff0000, v88
	v_lshlrev_b32_e32 v222, 16, v89
	v_and_b32_e32 v223, 0xffff0000, v89
	v_lshlrev_b32_e32 v224, 16, v90
	v_and_b32_e32 v225, 0xffff0000, v90
	v_lshlrev_b32_e32 v226, 16, v91
	v_and_b32_e32 v227, 0xffff0000, v91
	v_lshlrev_b32_e32 v236, 16, v120
	v_and_b32_e32 v237, 0xffff0000, v120
	v_lshlrev_b32_e32 v238, 16, v121
	v_and_b32_e32 v239, 0xffff0000, v121
	v_lshlrev_b32_e32 v240, 16, v122
	v_and_b32_e32 v241, 0xffff0000, v122
	v_lshlrev_b32_e32 v242, 16, v123
	v_and_b32_e32 v243, 0xffff0000, v123
	v_pk_mul_f32 v[244:245], v[140:141], v[204:205]
	v_pk_fma_f32 v[244:245], v[132:133], v[228:229], v[244:245]
	v_pk_fma_f32 v[244:245], v[148:149], v[220:221], v[244:245]
	v_pk_mul_f32 v[244:245], v[244:245], v[236:237]
	v_cvt_pk_bf16_f32 v216, v244, v245
	v_pk_mul_f32 v[246:247], v[142:143], v[206:207]
	v_pk_fma_f32 v[246:247], v[134:135], v[230:231], v[246:247]
	v_pk_fma_f32 v[246:247], v[150:151], v[222:223], v[246:247]
	v_pk_mul_f32 v[246:247], v[246:247], v[238:239]
	v_cvt_pk_bf16_f32 v217, v246, v247
	v_pk_mul_f32 v[244:245], v[144:145], v[208:209]
	v_pk_fma_f32 v[244:245], v[136:137], v[232:233], v[244:245]
	v_pk_fma_f32 v[244:245], v[152:153], v[224:225], v[244:245]
	v_pk_mul_f32 v[244:245], v[244:245], v[240:241]
	v_cvt_pk_bf16_f32 v218, v244, v245
	v_pk_mul_f32 v[246:247], v[146:147], v[210:211]
	v_pk_fma_f32 v[246:247], v[138:139], v[234:235], v[246:247]
	v_pk_fma_f32 v[246:247], v[154:155], v[226:227], v[246:247]
	v_pk_mul_f32 v[246:247], v[246:247], v[242:243]
	v_cvt_pk_bf16_f32 v219, v246, v247
	s_add_u32 s18, s16, 0x9c00
	s_addc_u32 s19, s17, 0
	global_store_dwordx4 v2, v[216:219], s[18:19] nt
	v_lshlrev_b32_e32 v228, 16, v92
	v_and_b32_e32 v229, 0xffff0000, v92
	v_lshlrev_b32_e32 v230, 16, v93
	v_and_b32_e32 v231, 0xffff0000, v93
	v_lshlrev_b32_e32 v232, 16, v94
	v_and_b32_e32 v233, 0xffff0000, v94
	v_lshlrev_b32_e32 v234, 16, v95
	v_and_b32_e32 v235, 0xffff0000, v95
	v_lshlrev_b32_e32 v236, 16, v124
	v_and_b32_e32 v237, 0xffff0000, v124
	v_lshlrev_b32_e32 v238, 16, v125
	v_and_b32_e32 v239, 0xffff0000, v125
	v_lshlrev_b32_e32 v240, 16, v126
	v_and_b32_e32 v241, 0xffff0000, v126
	v_lshlrev_b32_e32 v242, 16, v127
	v_and_b32_e32 v243, 0xffff0000, v127
	v_pk_mul_f32 v[244:245], v[140:141], v[220:221]
	v_pk_fma_f32 v[244:245], v[132:133], v[204:205], v[244:245]
	v_pk_fma_f32 v[244:245], v[148:149], v[228:229], v[244:245]
	v_pk_mul_f32 v[244:245], v[244:245], v[236:237]
	v_cvt_pk_bf16_f32 v212, v244, v245
	v_pk_mul_f32 v[246:247], v[142:143], v[222:223]
	v_pk_fma_f32 v[246:247], v[134:135], v[206:207], v[246:247]
	v_pk_fma_f32 v[246:247], v[150:151], v[230:231], v[246:247]
	v_pk_mul_f32 v[246:247], v[246:247], v[238:239]
	v_cvt_pk_bf16_f32 v213, v246, v247
	v_pk_mul_f32 v[244:245], v[144:145], v[224:225]
	v_pk_fma_f32 v[244:245], v[136:137], v[208:209], v[244:245]
	v_pk_fma_f32 v[244:245], v[152:153], v[232:233], v[244:245]
	v_pk_mul_f32 v[244:245], v[244:245], v[240:241]
	v_cvt_pk_bf16_f32 v214, v244, v245
	v_pk_mul_f32 v[246:247], v[146:147], v[226:227]
	v_pk_fma_f32 v[246:247], v[138:139], v[210:211], v[246:247]
	v_pk_fma_f32 v[246:247], v[154:155], v[234:235], v[246:247]
	v_pk_mul_f32 v[246:247], v[246:247], v[242:243]
	v_cvt_pk_bf16_f32 v215, v246, v247
	s_add_u32 s18, s16, 0xa800
	s_addc_u32 s19, s17, 0
	global_store_dwordx4 v2, v[212:215], s[18:19] nt
	v_lshlrev_b32_e32 v204, 16, v96
	v_and_b32_e32 v205, 0xffff0000, v96
	v_lshlrev_b32_e32 v206, 16, v97
	v_and_b32_e32 v207, 0xffff0000, v97
	v_lshlrev_b32_e32 v208, 16, v98
	v_and_b32_e32 v209, 0xffff0000, v98
	v_lshlrev_b32_e32 v210, 16, v99
	v_and_b32_e32 v211, 0xffff0000, v99
	v_lshlrev_b32_e32 v236, 16, v128
	v_and_b32_e32 v237, 0xffff0000, v128
	v_lshlrev_b32_e32 v238, 16, v129
	v_and_b32_e32 v239, 0xffff0000, v129
	v_lshlrev_b32_e32 v240, 16, v130
	v_and_b32_e32 v241, 0xffff0000, v130
	v_lshlrev_b32_e32 v242, 16, v131
	v_and_b32_e32 v243, 0xffff0000, v131
	v_pk_mul_f32 v[244:245], v[140:141], v[228:229]
	v_pk_fma_f32 v[244:245], v[132:133], v[220:221], v[244:245]
	v_pk_fma_f32 v[244:245], v[148:149], v[204:205], v[244:245]
	v_pk_mul_f32 v[244:245], v[244:245], v[236:237]
	v_cvt_pk_bf16_f32 v216, v244, v245
	v_pk_mul_f32 v[246:247], v[142:143], v[230:231]
	v_pk_fma_f32 v[246:247], v[134:135], v[222:223], v[246:247]
	v_pk_fma_f32 v[246:247], v[150:151], v[206:207], v[246:247]
	v_pk_mul_f32 v[246:247], v[246:247], v[238:239]
	v_cvt_pk_bf16_f32 v217, v246, v247
	v_pk_mul_f32 v[244:245], v[144:145], v[232:233]
	v_pk_fma_f32 v[244:245], v[136:137], v[224:225], v[244:245]
	v_pk_fma_f32 v[244:245], v[152:153], v[208:209], v[244:245]
	v_pk_mul_f32 v[244:245], v[244:245], v[240:241]
	v_cvt_pk_bf16_f32 v218, v244, v245
	v_pk_mul_f32 v[246:247], v[146:147], v[234:235]
	v_pk_fma_f32 v[246:247], v[138:139], v[226:227], v[246:247]
	v_pk_fma_f32 v[246:247], v[154:155], v[210:211], v[246:247]
	v_pk_mul_f32 v[246:247], v[246:247], v[242:243]
	v_cvt_pk_bf16_f32 v219, v246, v247
	s_add_u32 s18, s16, 0xb400
	s_addc_u32 s19, s17, 0
	global_store_dwordx4 v2, v[216:219], s[18:19] nt
	s_add_u32 s18, s12, 0x4400
	s_addc_u32 s19, s13, 0
	s_add_u32 s30, s14, 0x4400
	s_addc_u32 s31, s15, 0
	global_load_dwordx4 v[68:71], v2, s[18:19] nt
	global_load_dwordx4 v[100:103], v2, s[30:31] nt
	s_add_u32 s18, s12, 0x4c00
	s_addc_u32 s19, s13, 0
	s_add_u32 s30, s14, 0x4c00
	s_addc_u32 s31, s15, 0
	global_load_dwordx4 v[72:75], v2, s[18:19] nt
	global_load_dwordx4 v[104:107], v2, s[30:31] nt
	s_add_u32 s18, s12, 0x5400
	s_addc_u32 s19, s13, 0
	s_add_u32 s30, s14, 0x5400
	s_addc_u32 s31, s15, 0
	global_load_dwordx4 v[76:79], v2, s[18:19] nt
	global_load_dwordx4 v[108:111], v2, s[30:31] nt
	s_add_u32 s18, s12, 0x5c00
	s_addc_u32 s19, s13, 0
	s_add_u32 s30, s14, 0x5c00
	s_addc_u32 s31, s15, 0
	global_load_dwordx4 v[80:83], v2, s[18:19] nt
	global_load_dwordx4 v[112:115], v2, s[30:31] nt
	s_add_u32 s18, s12, 0x6400
	s_addc_u32 s19, s13, 0
	s_add_u32 s30, s14, 0x6400
	s_addc_u32 s31, s15, 0
	global_load_dwordx4 v[84:87], v2, s[18:19] nt
	global_load_dwordx4 v[116:119], v2, s[30:31] nt
	s_add_u32 s18, s12, 0x6c00
	s_addc_u32 s19, s13, 0
	s_add_u32 s30, s14, 0x6c00
	s_addc_u32 s31, s15, 0
	global_load_dwordx4 v[88:91], v2, s[18:19] nt
	global_load_dwordx4 v[120:123], v2, s[30:31] nt
	s_add_u32 s18, s12, 0x7400
	s_addc_u32 s19, s13, 0
	s_add_u32 s30, s14, 0x7400
	s_addc_u32 s31, s15, 0
	global_load_dwordx4 v[92:95], v2, s[18:19] nt
	global_load_dwordx4 v[124:127], v2, s[30:31] nt
	s_add_u32 s18, s12, 0x7c00
	s_addc_u32 s19, s13, 0
	s_add_u32 s30, s14, 0x7c00
	s_addc_u32 s31, s15, 0
	global_load_dwordx4 v[96:99], v2, s[18:19] nt
	global_load_dwordx4 v[128:131], v2, s[30:31] nt
	s_waitcnt vmcnt(24)
	s_cmp_lg_u32 s21, 0
	s_cbranch_scc1 .Lcv_nz1
	v_mov_b32_e32 v188, 0
	v_mov_b32_e32 v189, 0
	v_mov_b32_e32 v190, 0
	v_mov_b32_e32 v191, 0
	v_mov_b32_e32 v196, 0
	v_mov_b32_e32 v197, 0
	v_mov_b32_e32 v198, 0
	v_mov_b32_e32 v199, 0
.Lcv_nz1:
	v_lshlrev_b32_e32 v220, 16, v196
	v_and_b32_e32 v221, 0xffff0000, v196
	v_lshlrev_b32_e32 v222, 16, v197
	v_and_b32_e32 v223, 0xffff0000, v197
	v_lshlrev_b32_e32 v224, 16, v198
	v_and_b32_e32 v225, 0xffff0000, v198
	v_lshlrev_b32_e32 v226, 16, v199
	v_and_b32_e32 v227, 0xffff0000, v199
	v_lshlrev_b32_e32 v228, 16, v188
	v_and_b32_e32 v229, 0xffff0000, v188
	v_lshlrev_b32_e32 v230, 16, v189
	v_and_b32_e32 v231, 0xffff0000, v189
	v_lshlrev_b32_e32 v232, 16, v190
	v_and_b32_e32 v233, 0xffff0000, v190
	v_lshlrev_b32_e32 v234, 16, v191
	v_and_b32_e32 v235, 0xffff0000, v191
	v_lshlrev_b32_e32 v204, 16, v4
	v_and_b32_e32 v205, 0xffff0000, v4
	v_lshlrev_b32_e32 v206, 16, v5
	v_and_b32_e32 v207, 0xffff0000, v5
	v_lshlrev_b32_e32 v208, 16, v6
	v_and_b32_e32 v209, 0xffff0000, v6
	v_lshlrev_b32_e32 v210, 16, v7
	v_and_b32_e32 v211, 0xffff0000, v7
	v_lshlrev_b32_e32 v236, 16, v36
	v_and_b32_e32 v237, 0xffff0000, v36
	v_lshlrev_b32_e32 v238, 16, v37
	v_and_b32_e32 v239, 0xffff0000, v37
	v_lshlrev_b32_e32 v240, 16, v38
	v_and_b32_e32 v241, 0xffff0000, v38
	v_lshlrev_b32_e32 v242, 16, v39
	v_and_b32_e32 v243, 0xffff0000, v39
	v_pk_mul_f32 v[244:245], v[164:165], v[228:229]
	v_pk_fma_f32 v[244:245], v[156:157], v[220:221], v[244:245]
	v_pk_fma_f32 v[244:245], v[172:173], v[204:205], v[244:245]
	v_pk_mul_f32 v[244:245], v[244:245], v[236:237]
	v_cvt_pk_bf16_f32 v212, v244, v245
	v_pk_mul_f32 v[246:247], v[166:167], v[230:231]
	v_pk_fma_f32 v[246:247], v[158:159], v[222:223], v[246:247]
	v_pk_fma_f32 v[246:247], v[174:175], v[206:207], v[246:247]
	v_pk_mul_f32 v[246:247], v[246:247], v[238:239]
	v_cvt_pk_bf16_f32 v213, v246, v247
	v_pk_mul_f32 v[244:245], v[168:169], v[232:233]
	v_pk_fma_f32 v[244:245], v[160:161], v[224:225], v[244:245]
	v_pk_fma_f32 v[244:245], v[176:177], v[208:209], v[244:245]
	v_pk_mul_f32 v[244:245], v[244:245], v[240:241]
	v_cvt_pk_bf16_f32 v214, v244, v245
	v_pk_mul_f32 v[246:247], v[170:171], v[234:235]
	v_pk_fma_f32 v[246:247], v[162:163], v[226:227], v[246:247]
	v_pk_fma_f32 v[246:247], v[178:179], v[210:211], v[246:247]
	v_pk_mul_f32 v[246:247], v[246:247], v[242:243]
	v_cvt_pk_bf16_f32 v215, v246, v247
	s_add_u32 s18, s16, 0x400
	s_addc_u32 s19, s17, 0
	global_store_dwordx4 v2, v[212:215], s[18:19] nt
	v_lshlrev_b32_e32 v220, 16, v8
	v_and_b32_e32 v221, 0xffff0000, v8
	v_lshlrev_b32_e32 v222, 16, v9
	v_and_b32_e32 v223, 0xffff0000, v9
	v_lshlrev_b32_e32 v224, 16, v10
	v_and_b32_e32 v225, 0xffff0000, v10
	v_lshlrev_b32_e32 v226, 16, v11
	v_and_b32_e32 v227, 0xffff0000, v11
	v_lshlrev_b32_e32 v236, 16, v40
	v_and_b32_e32 v237, 0xffff0000, v40
	v_lshlrev_b32_e32 v238, 16, v41
	v_and_b32_e32 v239, 0xffff0000, v41
	v_lshlrev_b32_e32 v240, 16, v42
	v_and_b32_e32 v241, 0xffff0000, v42
	v_lshlrev_b32_e32 v242, 16, v43
	v_and_b32_e32 v243, 0xffff0000, v43
	v_pk_mul_f32 v[244:245], v[164:165], v[204:205]
	v_pk_fma_f32 v[244:245], v[156:157], v[228:229], v[244:245]
	v_pk_fma_f32 v[244:245], v[172:173], v[220:221], v[244:245]
	v_pk_mul_f32 v[244:245], v[244:245], v[236:237]
	v_cvt_pk_bf16_f32 v216, v244, v245
	v_pk_mul_f32 v[246:247], v[166:167], v[206:207]
	v_pk_fma_f32 v[246:247], v[158:159], v[230:231], v[246:247]
	v_pk_fma_f32 v[246:247], v[174:175], v[222:223], v[246:247]
	v_pk_mul_f32 v[246:247], v[246:247], v[238:239]
	v_cvt_pk_bf16_f32 v217, v246, v247
	v_pk_mul_f32 v[244:245], v[168:169], v[208:209]
	v_pk_fma_f32 v[244:245], v[160:161], v[232:233], v[244:245]
	v_pk_fma_f32 v[244:245], v[176:177], v[224:225], v[244:245]
	v_pk_mul_f32 v[244:245], v[244:245], v[240:241]
	v_cvt_pk_bf16_f32 v218, v244, v245
	v_pk_mul_f32 v[246:247], v[170:171], v[210:211]
	v_pk_fma_f32 v[246:247], v[162:163], v[234:235], v[246:247]
	v_pk_fma_f32 v[246:247], v[178:179], v[226:227], v[246:247]
	v_pk_mul_f32 v[246:247], v[246:247], v[242:243]
	v_cvt_pk_bf16_f32 v219, v246, v247
	s_add_u32 s18, s16, 0x1000
	s_addc_u32 s19, s17, 0
	global_store_dwordx4 v2, v[216:219], s[18:19] nt
	v_lshlrev_b32_e32 v228, 16, v12
	v_and_b32_e32 v229, 0xffff0000, v12
	v_lshlrev_b32_e32 v230, 16, v13
	v_and_b32_e32 v231, 0xffff0000, v13
	v_lshlrev_b32_e32 v232, 16, v14
	v_and_b32_e32 v233, 0xffff0000, v14
	v_lshlrev_b32_e32 v234, 16, v15
	v_and_b32_e32 v235, 0xffff0000, v15
	v_lshlrev_b32_e32 v236, 16, v44
	v_and_b32_e32 v237, 0xffff0000, v44
	v_lshlrev_b32_e32 v238, 16, v45
	v_and_b32_e32 v239, 0xffff0000, v45
	v_lshlrev_b32_e32 v240, 16, v46
	v_and_b32_e32 v241, 0xffff0000, v46
	v_lshlrev_b32_e32 v242, 16, v47
	v_and_b32_e32 v243, 0xffff0000, v47
	v_pk_mul_f32 v[244:245], v[164:165], v[220:221]
	v_pk_fma_f32 v[244:245], v[156:157], v[204:205], v[244:245]
	v_pk_fma_f32 v[244:245], v[172:173], v[228:229], v[244:245]
	v_pk_mul_f32 v[244:245], v[244:245], v[236:237]
	v_cvt_pk_bf16_f32 v212, v244, v245
	v_pk_mul_f32 v[246:247], v[166:167], v[222:223]
	v_pk_fma_f32 v[246:247], v[158:159], v[206:207], v[246:247]
	v_pk_fma_f32 v[246:247], v[174:175], v[230:231], v[246:247]
	v_pk_mul_f32 v[246:247], v[246:247], v[238:239]
	v_cvt_pk_bf16_f32 v213, v246, v247
	v_pk_mul_f32 v[244:245], v[168:169], v[224:225]
	v_pk_fma_f32 v[244:245], v[160:161], v[208:209], v[244:245]
	v_pk_fma_f32 v[244:245], v[176:177], v[232:233], v[244:245]
	v_pk_mul_f32 v[244:245], v[244:245], v[240:241]
	v_cvt_pk_bf16_f32 v214, v244, v245
	v_pk_mul_f32 v[246:247], v[170:171], v[226:227]
	v_pk_fma_f32 v[246:247], v[162:163], v[210:211], v[246:247]
	v_pk_fma_f32 v[246:247], v[178:179], v[234:235], v[246:247]
	v_pk_mul_f32 v[246:247], v[246:247], v[242:243]
	v_cvt_pk_bf16_f32 v215, v246, v247
	s_add_u32 s18, s16, 0x1c00
	s_addc_u32 s19, s17, 0
	global_store_dwordx4 v2, v[212:215], s[18:19] nt
	v_lshlrev_b32_e32 v204, 16, v16
	v_and_b32_e32 v205, 0xffff0000, v16
	v_lshlrev_b32_e32 v206, 16, v17
	v_and_b32_e32 v207, 0xffff0000, v17
	v_lshlrev_b32_e32 v208, 16, v18
	v_and_b32_e32 v209, 0xffff0000, v18
	v_lshlrev_b32_e32 v210, 16, v19
	v_and_b32_e32 v211, 0xffff0000, v19
	v_lshlrev_b32_e32 v236, 16, v48
	v_and_b32_e32 v237, 0xffff0000, v48
	v_lshlrev_b32_e32 v238, 16, v49
	v_and_b32_e32 v239, 0xffff0000, v49
	v_lshlrev_b32_e32 v240, 16, v50
	v_and_b32_e32 v241, 0xffff0000, v50
	v_lshlrev_b32_e32 v242, 16, v51
	v_and_b32_e32 v243, 0xffff0000, v51
	v_pk_mul_f32 v[244:245], v[164:165], v[228:229]
	v_pk_fma_f32 v[244:245], v[156:157], v[220:221], v[244:245]
	v_pk_fma_f32 v[244:245], v[172:173], v[204:205], v[244:245]
	v_pk_mul_f32 v[244:245], v[244:245], v[236:237]
	v_cvt_pk_bf16_f32 v216, v244, v245
	v_pk_mul_f32 v[246:247], v[166:167], v[230:231]
	v_pk_fma_f32 v[246:247], v[158:159], v[222:223], v[246:247]
	v_pk_fma_f32 v[246:247], v[174:175], v[206:207], v[246:247]
	v_pk_mul_f32 v[246:247], v[246:247], v[238:239]
	v_cvt_pk_bf16_f32 v217, v246, v247
	v_pk_mul_f32 v[244:245], v[168:169], v[232:233]
	v_pk_fma_f32 v[244:245], v[160:161], v[224:225], v[244:245]
	v_pk_fma_f32 v[244:245], v[176:177], v[208:209], v[244:245]
	v_pk_mul_f32 v[244:245], v[244:245], v[240:241]
	v_cvt_pk_bf16_f32 v218, v244, v245
	v_pk_mul_f32 v[246:247], v[170:171], v[234:235]
	v_pk_fma_f32 v[246:247], v[162:163], v[226:227], v[246:247]
	v_pk_fma_f32 v[246:247], v[178:179], v[210:211], v[246:247]
	v_pk_mul_f32 v[246:247], v[246:247], v[242:243]
	v_cvt_pk_bf16_f32 v219, v246, v247
	s_add_u32 s18, s16, 0x2800
	s_addc_u32 s19, s17, 0
	global_store_dwordx4 v2, v[216:219], s[18:19] nt
	v_lshlrev_b32_e32 v220, 16, v20
	v_and_b32_e32 v221, 0xffff0000, v20
	v_lshlrev_b32_e32 v222, 16, v21
	v_and_b32_e32 v223, 0xffff0000, v21
	v_lshlrev_b32_e32 v224, 16, v22
	v_and_b32_e32 v225, 0xffff0000, v22
	v_lshlrev_b32_e32 v226, 16, v23
	v_and_b32_e32 v227, 0xffff0000, v23
	v_lshlrev_b32_e32 v236, 16, v52
	v_and_b32_e32 v237, 0xffff0000, v52
	v_lshlrev_b32_e32 v238, 16, v53
	v_and_b32_e32 v239, 0xffff0000, v53
	v_lshlrev_b32_e32 v240, 16, v54
	v_and_b32_e32 v241, 0xffff0000, v54
	v_lshlrev_b32_e32 v242, 16, v55
	v_and_b32_e32 v243, 0xffff0000, v55
	v_pk_mul_f32 v[244:245], v[164:165], v[204:205]
	v_pk_fma_f32 v[244:245], v[156:157], v[228:229], v[244:245]
	v_pk_fma_f32 v[244:245], v[172:173], v[220:221], v[244:245]
	v_pk_mul_f32 v[244:245], v[244:245], v[236:237]
	v_cvt_pk_bf16_f32 v212, v244, v245
	v_pk_mul_f32 v[246:247], v[166:167], v[206:207]
	v_pk_fma_f32 v[246:247], v[158:159], v[230:231], v[246:247]
	v_pk_fma_f32 v[246:247], v[174:175], v[222:223], v[246:247]
	v_pk_mul_f32 v[246:247], v[246:247], v[238:239]
	v_cvt_pk_bf16_f32 v213, v246, v247
	v_pk_mul_f32 v[244:245], v[168:169], v[208:209]
	v_pk_fma_f32 v[244:245], v[160:161], v[232:233], v[244:245]
	v_pk_fma_f32 v[244:245], v[176:177], v[224:225], v[244:245]
	v_pk_mul_f32 v[244:245], v[244:245], v[240:241]
	v_cvt_pk_bf16_f32 v214, v244, v245
	v_pk_mul_f32 v[246:247], v[170:171], v[210:211]
	v_pk_fma_f32 v[246:247], v[162:163], v[234:235], v[246:247]
	v_pk_fma_f32 v[246:247], v[178:179], v[226:227], v[246:247]
	v_pk_mul_f32 v[246:247], v[246:247], v[242:243]
	v_cvt_pk_bf16_f32 v215, v246, v247
	s_add_u32 s18, s16, 0x3400
	s_addc_u32 s19, s17, 0
	global_store_dwordx4 v2, v[212:215], s[18:19] nt
	v_lshlrev_b32_e32 v228, 16, v24
	v_and_b32_e32 v229, 0xffff0000, v24
	v_lshlrev_b32_e32 v230, 16, v25
	v_and_b32_e32 v231, 0xffff0000, v25
	v_lshlrev_b32_e32 v232, 16, v26
	v_and_b32_e32 v233, 0xffff0000, v26
	v_lshlrev_b32_e32 v234, 16, v27
	v_and_b32_e32 v235, 0xffff0000, v27
	v_lshlrev_b32_e32 v236, 16, v56
	v_and_b32_e32 v237, 0xffff0000, v56
	v_lshlrev_b32_e32 v238, 16, v57
	v_and_b32_e32 v239, 0xffff0000, v57
	v_lshlrev_b32_e32 v240, 16, v58
	v_and_b32_e32 v241, 0xffff0000, v58
	v_lshlrev_b32_e32 v242, 16, v59
	v_and_b32_e32 v243, 0xffff0000, v59
	v_pk_mul_f32 v[244:245], v[164:165], v[220:221]
	v_pk_fma_f32 v[244:245], v[156:157], v[204:205], v[244:245]
	v_pk_fma_f32 v[244:245], v[172:173], v[228:229], v[244:245]
	v_pk_mul_f32 v[244:245], v[244:245], v[236:237]
	v_cvt_pk_bf16_f32 v216, v244, v245
	v_pk_mul_f32 v[246:247], v[166:167], v[222:223]
	v_pk_fma_f32 v[246:247], v[158:159], v[206:207], v[246:247]
	v_pk_fma_f32 v[246:247], v[174:175], v[230:231], v[246:247]
	v_pk_mul_f32 v[246:247], v[246:247], v[238:239]
	v_cvt_pk_bf16_f32 v217, v246, v247
	v_pk_mul_f32 v[244:245], v[168:169], v[224:225]
	v_pk_fma_f32 v[244:245], v[160:161], v[208:209], v[244:245]
	v_pk_fma_f32 v[244:245], v[176:177], v[232:233], v[244:245]
	v_pk_mul_f32 v[244:245], v[244:245], v[240:241]
	v_cvt_pk_bf16_f32 v218, v244, v245
	v_pk_mul_f32 v[246:247], v[170:171], v[226:227]
	v_pk_fma_f32 v[246:247], v[162:163], v[210:211], v[246:247]
	v_pk_fma_f32 v[246:247], v[178:179], v[234:235], v[246:247]
	v_pk_mul_f32 v[246:247], v[246:247], v[242:243]
	v_cvt_pk_bf16_f32 v219, v246, v247
	s_add_u32 s18, s16, 0x4000
	s_addc_u32 s19, s17, 0
	global_store_dwordx4 v2, v[216:219], s[18:19] nt
	v_lshlrev_b32_e32 v204, 16, v28
	v_and_b32_e32 v205, 0xffff0000, v28
	v_lshlrev_b32_e32 v206, 16, v29
	v_and_b32_e32 v207, 0xffff0000, v29
	v_lshlrev_b32_e32 v208, 16, v30
	v_and_b32_e32 v209, 0xffff0000, v30
	v_lshlrev_b32_e32 v210, 16, v31
	v_and_b32_e32 v211, 0xffff0000, v31
	v_lshlrev_b32_e32 v236, 16, v60
	v_and_b32_e32 v237, 0xffff0000, v60
	v_lshlrev_b32_e32 v238, 16, v61
	v_and_b32_e32 v239, 0xffff0000, v61
	v_lshlrev_b32_e32 v240, 16, v62
	v_and_b32_e32 v241, 0xffff0000, v62
	v_lshlrev_b32_e32 v242, 16, v63
	v_and_b32_e32 v243, 0xffff0000, v63
	v_pk_mul_f32 v[244:245], v[164:165], v[228:229]
	v_pk_fma_f32 v[244:245], v[156:157], v[220:221], v[244:245]
	v_pk_fma_f32 v[244:245], v[172:173], v[204:205], v[244:245]
	v_pk_mul_f32 v[244:245], v[244:245], v[236:237]
	v_cvt_pk_bf16_f32 v212, v244, v245
	v_pk_mul_f32 v[246:247], v[166:167], v[230:231]
	v_pk_fma_f32 v[246:247], v[158:159], v[222:223], v[246:247]
	v_pk_fma_f32 v[246:247], v[174:175], v[206:207], v[246:247]
	v_pk_mul_f32 v[246:247], v[246:247], v[238:239]
	v_cvt_pk_bf16_f32 v213, v246, v247
	v_pk_mul_f32 v[244:245], v[168:169], v[232:233]
	v_pk_fma_f32 v[244:245], v[160:161], v[224:225], v[244:245]
	v_pk_fma_f32 v[244:245], v[176:177], v[208:209], v[244:245]
	v_pk_mul_f32 v[244:245], v[244:245], v[240:241]
	v_cvt_pk_bf16_f32 v214, v244, v245
	v_pk_mul_f32 v[246:247], v[170:171], v[234:235]
	v_pk_fma_f32 v[246:247], v[162:163], v[226:227], v[246:247]
	v_pk_fma_f32 v[246:247], v[178:179], v[210:211], v[246:247]
	v_pk_mul_f32 v[246:247], v[246:247], v[242:243]
	v_cvt_pk_bf16_f32 v215, v246, v247
	s_add_u32 s18, s16, 0x4c00
	s_addc_u32 s19, s17, 0
	global_store_dwordx4 v2, v[212:215], s[18:19] nt
	v_lshlrev_b32_e32 v220, 16, v32
	v_and_b32_e32 v221, 0xffff0000, v32
	v_lshlrev_b32_e32 v222, 16, v33
	v_and_b32_e32 v223, 0xffff0000, v33
	v_lshlrev_b32_e32 v224, 16, v34
	v_and_b32_e32 v225, 0xffff0000, v34
	v_lshlrev_b32_e32 v226, 16, v35
	v_and_b32_e32 v227, 0xffff0000, v35
	v_lshlrev_b32_e32 v236, 16, v64
	v_and_b32_e32 v237, 0xffff0000, v64
	v_lshlrev_b32_e32 v238, 16, v65
	v_and_b32_e32 v239, 0xffff0000, v65
	v_lshlrev_b32_e32 v240, 16, v66
	v_and_b32_e32 v241, 0xffff0000, v66
	v_lshlrev_b32_e32 v242, 16, v67
	v_and_b32_e32 v243, 0xffff0000, v67
	v_pk_mul_f32 v[244:245], v[164:165], v[204:205]
	v_pk_fma_f32 v[244:245], v[156:157], v[228:229], v[244:245]
	v_pk_fma_f32 v[244:245], v[172:173], v[220:221], v[244:245]
	v_pk_mul_f32 v[244:245], v[244:245], v[236:237]
	v_cvt_pk_bf16_f32 v216, v244, v245
	v_pk_mul_f32 v[246:247], v[166:167], v[206:207]
	v_pk_fma_f32 v[246:247], v[158:159], v[230:231], v[246:247]
	v_pk_fma_f32 v[246:247], v[174:175], v[222:223], v[246:247]
	v_pk_mul_f32 v[246:247], v[246:247], v[238:239]
	v_cvt_pk_bf16_f32 v217, v246, v247
	v_pk_mul_f32 v[244:245], v[168:169], v[208:209]
	v_pk_fma_f32 v[244:245], v[160:161], v[232:233], v[244:245]
	v_pk_fma_f32 v[244:245], v[176:177], v[224:225], v[244:245]
	v_pk_mul_f32 v[244:245], v[244:245], v[240:241]
	v_cvt_pk_bf16_f32 v218, v244, v245
	v_pk_mul_f32 v[246:247], v[170:171], v[210:211]
	v_pk_fma_f32 v[246:247], v[162:163], v[234:235], v[246:247]
	v_pk_fma_f32 v[246:247], v[178:179], v[226:227], v[246:247]
	v_pk_mul_f32 v[246:247], v[246:247], v[242:243]
	v_cvt_pk_bf16_f32 v219, v246, v247
	s_add_u32 s18, s16, 0x5800
	s_addc_u32 s19, s17, 0
	global_store_dwordx4 v2, v[216:219], s[18:19] nt
	s_waitcnt vmcnt(8)
	v_lshlrev_b32_e32 v228, 16, v68
	v_and_b32_e32 v229, 0xffff0000, v68
	v_lshlrev_b32_e32 v230, 16, v69
	v_and_b32_e32 v231, 0xffff0000, v69
	v_lshlrev_b32_e32 v232, 16, v70
	v_and_b32_e32 v233, 0xffff0000, v70
	v_lshlrev_b32_e32 v234, 16, v71
	v_and_b32_e32 v235, 0xffff0000, v71
	v_lshlrev_b32_e32 v236, 16, v100
	v_and_b32_e32 v237, 0xffff0000, v100
	v_lshlrev_b32_e32 v238, 16, v101
	v_and_b32_e32 v239, 0xffff0000, v101
	v_lshlrev_b32_e32 v240, 16, v102
	v_and_b32_e32 v241, 0xffff0000, v102
	v_lshlrev_b32_e32 v242, 16, v103
	v_and_b32_e32 v243, 0xffff0000, v103
	v_pk_mul_f32 v[244:245], v[164:165], v[220:221]
	v_pk_fma_f32 v[244:245], v[156:157], v[204:205], v[244:245]
	v_pk_fma_f32 v[244:245], v[172:173], v[228:229], v[244:245]
	v_pk_mul_f32 v[244:245], v[244:245], v[236:237]
	v_cvt_pk_bf16_f32 v212, v244, v245
	v_pk_mul_f32 v[246:247], v[166:167], v[222:223]
	v_pk_fma_f32 v[246:247], v[158:159], v[206:207], v[246:247]
	v_pk_fma_f32 v[246:247], v[174:175], v[230:231], v[246:247]
	v_pk_mul_f32 v[246:247], v[246:247], v[238:239]
	v_cvt_pk_bf16_f32 v213, v246, v247
	v_pk_mul_f32 v[244:245], v[168:169], v[224:225]
	v_pk_fma_f32 v[244:245], v[160:161], v[208:209], v[244:245]
	v_pk_fma_f32 v[244:245], v[176:177], v[232:233], v[244:245]
	v_pk_mul_f32 v[244:245], v[244:245], v[240:241]
	v_cvt_pk_bf16_f32 v214, v244, v245
	v_pk_mul_f32 v[246:247], v[170:171], v[226:227]
	v_pk_fma_f32 v[246:247], v[162:163], v[210:211], v[246:247]
	v_pk_fma_f32 v[246:247], v[178:179], v[234:235], v[246:247]
	v_pk_mul_f32 v[246:247], v[246:247], v[242:243]
	v_cvt_pk_bf16_f32 v215, v246, v247
	s_add_u32 s18, s16, 0x6400
	s_addc_u32 s19, s17, 0
	global_store_dwordx4 v2, v[212:215], s[18:19] nt
	v_lshlrev_b32_e32 v204, 16, v72
	v_and_b32_e32 v205, 0xffff0000, v72
	v_lshlrev_b32_e32 v206, 16, v73
	v_and_b32_e32 v207, 0xffff0000, v73
	v_lshlrev_b32_e32 v208, 16, v74
	v_and_b32_e32 v209, 0xffff0000, v74
	v_lshlrev_b32_e32 v210, 16, v75
	v_and_b32_e32 v211, 0xffff0000, v75
	v_lshlrev_b32_e32 v236, 16, v104
	v_and_b32_e32 v237, 0xffff0000, v104
	v_lshlrev_b32_e32 v238, 16, v105
	v_and_b32_e32 v239, 0xffff0000, v105
	v_lshlrev_b32_e32 v240, 16, v106
	v_and_b32_e32 v241, 0xffff0000, v106
	v_lshlrev_b32_e32 v242, 16, v107
	v_and_b32_e32 v243, 0xffff0000, v107
	v_pk_mul_f32 v[244:245], v[164:165], v[228:229]
	v_pk_fma_f32 v[244:245], v[156:157], v[220:221], v[244:245]
	v_pk_fma_f32 v[244:245], v[172:173], v[204:205], v[244:245]
	v_pk_mul_f32 v[244:245], v[244:245], v[236:237]
	v_cvt_pk_bf16_f32 v216, v244, v245
	v_pk_mul_f32 v[246:247], v[166:167], v[230:231]
	v_pk_fma_f32 v[246:247], v[158:159], v[222:223], v[246:247]
	v_pk_fma_f32 v[246:247], v[174:175], v[206:207], v[246:247]
	v_pk_mul_f32 v[246:247], v[246:247], v[238:239]
	v_cvt_pk_bf16_f32 v217, v246, v247
	v_pk_mul_f32 v[244:245], v[168:169], v[232:233]
	v_pk_fma_f32 v[244:245], v[160:161], v[224:225], v[244:245]
	v_pk_fma_f32 v[244:245], v[176:177], v[208:209], v[244:245]
	v_pk_mul_f32 v[244:245], v[244:245], v[240:241]
	v_cvt_pk_bf16_f32 v218, v244, v245
	v_pk_mul_f32 v[246:247], v[170:171], v[234:235]
	v_pk_fma_f32 v[246:247], v[162:163], v[226:227], v[246:247]
	v_pk_fma_f32 v[246:247], v[178:179], v[210:211], v[246:247]
	v_pk_mul_f32 v[246:247], v[246:247], v[242:243]
	v_cvt_pk_bf16_f32 v219, v246, v247
	s_add_u32 s18, s16, 0x7000
	s_addc_u32 s19, s17, 0
	global_store_dwordx4 v2, v[216:219], s[18:19] nt
	v_lshlrev_b32_e32 v220, 16, v76
	v_and_b32_e32 v221, 0xffff0000, v76
	v_lshlrev_b32_e32 v222, 16, v77
	v_and_b32_e32 v223, 0xffff0000, v77
	v_lshlrev_b32_e32 v224, 16, v78
	v_and_b32_e32 v225, 0xffff0000, v78
	v_lshlrev_b32_e32 v226, 16, v79
	v_and_b32_e32 v227, 0xffff0000, v79
	v_lshlrev_b32_e32 v236, 16, v108
	v_and_b32_e32 v237, 0xffff0000, v108
	v_lshlrev_b32_e32 v238, 16, v109
	v_and_b32_e32 v239, 0xffff0000, v109
	v_lshlrev_b32_e32 v240, 16, v110
	v_and_b32_e32 v241, 0xffff0000, v110
	v_lshlrev_b32_e32 v242, 16, v111
	v_and_b32_e32 v243, 0xffff0000, v111
	v_pk_mul_f32 v[244:245], v[164:165], v[204:205]
	v_pk_fma_f32 v[244:245], v[156:157], v[228:229], v[244:245]
	v_pk_fma_f32 v[244:245], v[172:173], v[220:221], v[244:245]
	v_pk_mul_f32 v[244:245], v[244:245], v[236:237]
	v_cvt_pk_bf16_f32 v212, v244, v245
	v_pk_mul_f32 v[246:247], v[166:167], v[206:207]
	v_pk_fma_f32 v[246:247], v[158:159], v[230:231], v[246:247]
	v_pk_fma_f32 v[246:247], v[174:175], v[222:223], v[246:247]
	v_pk_mul_f32 v[246:247], v[246:247], v[238:239]
	v_cvt_pk_bf16_f32 v213, v246, v247
	v_pk_mul_f32 v[244:245], v[168:169], v[208:209]
	v_pk_fma_f32 v[244:245], v[160:161], v[232:233], v[244:245]
	v_pk_fma_f32 v[244:245], v[176:177], v[224:225], v[244:245]
	v_pk_mul_f32 v[244:245], v[244:245], v[240:241]
	v_cvt_pk_bf16_f32 v214, v244, v245
	v_pk_mul_f32 v[246:247], v[170:171], v[210:211]
	v_pk_fma_f32 v[246:247], v[162:163], v[234:235], v[246:247]
	v_pk_fma_f32 v[246:247], v[178:179], v[226:227], v[246:247]
	v_pk_mul_f32 v[246:247], v[246:247], v[242:243]
	v_cvt_pk_bf16_f32 v215, v246, v247
	s_add_u32 s18, s16, 0x7c00
	s_addc_u32 s19, s17, 0
	global_store_dwordx4 v2, v[212:215], s[18:19] nt
	v_lshlrev_b32_e32 v228, 16, v80
	v_and_b32_e32 v229, 0xffff0000, v80
	v_lshlrev_b32_e32 v230, 16, v81
	v_and_b32_e32 v231, 0xffff0000, v81
	v_lshlrev_b32_e32 v232, 16, v82
	v_and_b32_e32 v233, 0xffff0000, v82
	v_lshlrev_b32_e32 v234, 16, v83
	v_and_b32_e32 v235, 0xffff0000, v83
	v_lshlrev_b32_e32 v236, 16, v112
	v_and_b32_e32 v237, 0xffff0000, v112
	v_lshlrev_b32_e32 v238, 16, v113
	v_and_b32_e32 v239, 0xffff0000, v113
	v_lshlrev_b32_e32 v240, 16, v114
	v_and_b32_e32 v241, 0xffff0000, v114
	v_lshlrev_b32_e32 v242, 16, v115
	v_and_b32_e32 v243, 0xffff0000, v115
	v_pk_mul_f32 v[244:245], v[164:165], v[220:221]
	v_pk_fma_f32 v[244:245], v[156:157], v[204:205], v[244:245]
	v_pk_fma_f32 v[244:245], v[172:173], v[228:229], v[244:245]
	v_pk_mul_f32 v[244:245], v[244:245], v[236:237]
	v_cvt_pk_bf16_f32 v216, v244, v245
	v_pk_mul_f32 v[246:247], v[166:167], v[222:223]
	v_pk_fma_f32 v[246:247], v[158:159], v[206:207], v[246:247]
	v_pk_fma_f32 v[246:247], v[174:175], v[230:231], v[246:247]
	v_pk_mul_f32 v[246:247], v[246:247], v[238:239]
	v_cvt_pk_bf16_f32 v217, v246, v247
	v_pk_mul_f32 v[244:245], v[168:169], v[224:225]
	v_pk_fma_f32 v[244:245], v[160:161], v[208:209], v[244:245]
	v_pk_fma_f32 v[244:245], v[176:177], v[232:233], v[244:245]
	v_pk_mul_f32 v[244:245], v[244:245], v[240:241]
	v_cvt_pk_bf16_f32 v218, v244, v245
	v_pk_mul_f32 v[246:247], v[170:171], v[226:227]
	v_pk_fma_f32 v[246:247], v[162:163], v[210:211], v[246:247]
	v_pk_fma_f32 v[246:247], v[178:179], v[234:235], v[246:247]
	v_pk_mul_f32 v[246:247], v[246:247], v[242:243]
	v_cvt_pk_bf16_f32 v219, v246, v247
	s_add_u32 s18, s16, 0x8800
	s_addc_u32 s19, s17, 0
	global_store_dwordx4 v2, v[216:219], s[18:19] nt
	v_lshlrev_b32_e32 v204, 16, v84
	v_and_b32_e32 v205, 0xffff0000, v84
	v_lshlrev_b32_e32 v206, 16, v85
	v_and_b32_e32 v207, 0xffff0000, v85
	v_lshlrev_b32_e32 v208, 16, v86
	v_and_b32_e32 v209, 0xffff0000, v86
	v_lshlrev_b32_e32 v210, 16, v87
	v_and_b32_e32 v211, 0xffff0000, v87
	v_lshlrev_b32_e32 v236, 16, v116
	v_and_b32_e32 v237, 0xffff0000, v116
	v_lshlrev_b32_e32 v238, 16, v117
	v_and_b32_e32 v239, 0xffff0000, v117
	v_lshlrev_b32_e32 v240, 16, v118
	v_and_b32_e32 v241, 0xffff0000, v118
	v_lshlrev_b32_e32 v242, 16, v119
	v_and_b32_e32 v243, 0xffff0000, v119
	v_pk_mul_f32 v[244:245], v[164:165], v[228:229]
	v_pk_fma_f32 v[244:245], v[156:157], v[220:221], v[244:245]
	v_pk_fma_f32 v[244:245], v[172:173], v[204:205], v[244:245]
	v_pk_mul_f32 v[244:245], v[244:245], v[236:237]
	v_cvt_pk_bf16_f32 v212, v244, v245
	v_pk_mul_f32 v[246:247], v[166:167], v[230:231]
	v_pk_fma_f32 v[246:247], v[158:159], v[222:223], v[246:247]
	v_pk_fma_f32 v[246:247], v[174:175], v[206:207], v[246:247]
	v_pk_mul_f32 v[246:247], v[246:247], v[238:239]
	v_cvt_pk_bf16_f32 v213, v246, v247
	v_pk_mul_f32 v[244:245], v[168:169], v[232:233]
	v_pk_fma_f32 v[244:245], v[160:161], v[224:225], v[244:245]
	v_pk_fma_f32 v[244:245], v[176:177], v[208:209], v[244:245]
	v_pk_mul_f32 v[244:245], v[244:245], v[240:241]
	v_cvt_pk_bf16_f32 v214, v244, v245
	v_pk_mul_f32 v[246:247], v[170:171], v[234:235]
	v_pk_fma_f32 v[246:247], v[162:163], v[226:227], v[246:247]
	v_pk_fma_f32 v[246:247], v[178:179], v[210:211], v[246:247]
	v_pk_mul_f32 v[246:247], v[246:247], v[242:243]
	v_cvt_pk_bf16_f32 v215, v246, v247
	s_add_u32 s18, s16, 0x9400
	s_addc_u32 s19, s17, 0
	global_store_dwordx4 v2, v[212:215], s[18:19] nt
	v_lshlrev_b32_e32 v220, 16, v88
	v_and_b32_e32 v221, 0xffff0000, v88
	v_lshlrev_b32_e32 v222, 16, v89
	v_and_b32_e32 v223, 0xffff0000, v89
	v_lshlrev_b32_e32 v224, 16, v90
	v_and_b32_e32 v225, 0xffff0000, v90
	v_lshlrev_b32_e32 v226, 16, v91
	v_and_b32_e32 v227, 0xffff0000, v91
	v_lshlrev_b32_e32 v236, 16, v120
	v_and_b32_e32 v237, 0xffff0000, v120
	v_lshlrev_b32_e32 v238, 16, v121
	v_and_b32_e32 v239, 0xffff0000, v121
	v_lshlrev_b32_e32 v240, 16, v122
	v_and_b32_e32 v241, 0xffff0000, v122
	v_lshlrev_b32_e32 v242, 16, v123
	v_and_b32_e32 v243, 0xffff0000, v123
	v_pk_mul_f32 v[244:245], v[164:165], v[204:205]
	v_pk_fma_f32 v[244:245], v[156:157], v[228:229], v[244:245]
	v_pk_fma_f32 v[244:245], v[172:173], v[220:221], v[244:245]
	v_pk_mul_f32 v[244:245], v[244:245], v[236:237]
	v_cvt_pk_bf16_f32 v216, v244, v245
	v_pk_mul_f32 v[246:247], v[166:167], v[206:207]
	v_pk_fma_f32 v[246:247], v[158:159], v[230:231], v[246:247]
	v_pk_fma_f32 v[246:247], v[174:175], v[222:223], v[246:247]
	v_pk_mul_f32 v[246:247], v[246:247], v[238:239]
	v_cvt_pk_bf16_f32 v217, v246, v247
	v_pk_mul_f32 v[244:245], v[168:169], v[208:209]
	v_pk_fma_f32 v[244:245], v[160:161], v[232:233], v[244:245]
	v_pk_fma_f32 v[244:245], v[176:177], v[224:225], v[244:245]
	v_pk_mul_f32 v[244:245], v[244:245], v[240:241]
	v_cvt_pk_bf16_f32 v218, v244, v245
	v_pk_mul_f32 v[246:247], v[170:171], v[210:211]
	v_pk_fma_f32 v[246:247], v[162:163], v[234:235], v[246:247]
	v_pk_fma_f32 v[246:247], v[178:179], v[226:227], v[246:247]
	v_pk_mul_f32 v[246:247], v[246:247], v[242:243]
	v_cvt_pk_bf16_f32 v219, v246, v247
	s_add_u32 s18, s16, 0xa000
	s_addc_u32 s19, s17, 0
	global_store_dwordx4 v2, v[216:219], s[18:19] nt
	v_lshlrev_b32_e32 v228, 16, v92
	v_and_b32_e32 v229, 0xffff0000, v92
	v_lshlrev_b32_e32 v230, 16, v93
	v_and_b32_e32 v231, 0xffff0000, v93
	v_lshlrev_b32_e32 v232, 16, v94
	v_and_b32_e32 v233, 0xffff0000, v94
	v_lshlrev_b32_e32 v234, 16, v95
	v_and_b32_e32 v235, 0xffff0000, v95
	v_lshlrev_b32_e32 v236, 16, v124
	v_and_b32_e32 v237, 0xffff0000, v124
	v_lshlrev_b32_e32 v238, 16, v125
	v_and_b32_e32 v239, 0xffff0000, v125
	v_lshlrev_b32_e32 v240, 16, v126
	v_and_b32_e32 v241, 0xffff0000, v126
	v_lshlrev_b32_e32 v242, 16, v127
	v_and_b32_e32 v243, 0xffff0000, v127
	v_pk_mul_f32 v[244:245], v[164:165], v[220:221]
	v_pk_fma_f32 v[244:245], v[156:157], v[204:205], v[244:245]
	v_pk_fma_f32 v[244:245], v[172:173], v[228:229], v[244:245]
	v_pk_mul_f32 v[244:245], v[244:245], v[236:237]
	v_cvt_pk_bf16_f32 v212, v244, v245
	v_pk_mul_f32 v[246:247], v[166:167], v[222:223]
	v_pk_fma_f32 v[246:247], v[158:159], v[206:207], v[246:247]
	v_pk_fma_f32 v[246:247], v[174:175], v[230:231], v[246:247]
	v_pk_mul_f32 v[246:247], v[246:247], v[238:239]
	v_cvt_pk_bf16_f32 v213, v246, v247
	v_pk_mul_f32 v[244:245], v[168:169], v[224:225]
	v_pk_fma_f32 v[244:245], v[160:161], v[208:209], v[244:245]
	v_pk_fma_f32 v[244:245], v[176:177], v[232:233], v[244:245]
	v_pk_mul_f32 v[244:245], v[244:245], v[240:241]
	v_cvt_pk_bf16_f32 v214, v244, v245
	v_pk_mul_f32 v[246:247], v[170:171], v[226:227]
	v_pk_fma_f32 v[246:247], v[162:163], v[210:211], v[246:247]
	v_pk_fma_f32 v[246:247], v[178:179], v[234:235], v[246:247]
	v_pk_mul_f32 v[246:247], v[246:247], v[242:243]
	v_cvt_pk_bf16_f32 v215, v246, v247
	s_add_u32 s18, s16, 0xac00
	s_addc_u32 s19, s17, 0
	global_store_dwordx4 v2, v[212:215], s[18:19] nt
	v_lshlrev_b32_e32 v204, 16, v96
	v_and_b32_e32 v205, 0xffff0000, v96
	v_lshlrev_b32_e32 v206, 16, v97
	v_and_b32_e32 v207, 0xffff0000, v97
	v_lshlrev_b32_e32 v208, 16, v98
	v_and_b32_e32 v209, 0xffff0000, v98
	v_lshlrev_b32_e32 v210, 16, v99
	v_and_b32_e32 v211, 0xffff0000, v99
	v_lshlrev_b32_e32 v236, 16, v128
	v_and_b32_e32 v237, 0xffff0000, v128
	v_lshlrev_b32_e32 v238, 16, v129
	v_and_b32_e32 v239, 0xffff0000, v129
	v_lshlrev_b32_e32 v240, 16, v130
	v_and_b32_e32 v241, 0xffff0000, v130
	v_lshlrev_b32_e32 v242, 16, v131
	v_and_b32_e32 v243, 0xffff0000, v131
	v_pk_mul_f32 v[244:245], v[164:165], v[228:229]
	v_pk_fma_f32 v[244:245], v[156:157], v[220:221], v[244:245]
	v_pk_fma_f32 v[244:245], v[172:173], v[204:205], v[244:245]
	v_pk_mul_f32 v[244:245], v[244:245], v[236:237]
	v_cvt_pk_bf16_f32 v216, v244, v245
	v_pk_mul_f32 v[246:247], v[166:167], v[230:231]
	v_pk_fma_f32 v[246:247], v[158:159], v[222:223], v[246:247]
	v_pk_fma_f32 v[246:247], v[174:175], v[206:207], v[246:247]
	v_pk_mul_f32 v[246:247], v[246:247], v[238:239]
	v_cvt_pk_bf16_f32 v217, v246, v247
	v_pk_mul_f32 v[244:245], v[168:169], v[232:233]
	v_pk_fma_f32 v[244:245], v[160:161], v[224:225], v[244:245]
	v_pk_fma_f32 v[244:245], v[176:177], v[208:209], v[244:245]
	v_pk_mul_f32 v[244:245], v[244:245], v[240:241]
	v_cvt_pk_bf16_f32 v218, v244, v245
	v_pk_mul_f32 v[246:247], v[170:171], v[234:235]
	v_pk_fma_f32 v[246:247], v[162:163], v[226:227], v[246:247]
	v_pk_fma_f32 v[246:247], v[178:179], v[210:211], v[246:247]
	v_pk_mul_f32 v[246:247], v[246:247], v[242:243]
	v_cvt_pk_bf16_f32 v219, v246, v247
	s_add_u32 s18, s16, 0xb800
	s_addc_u32 s19, s17, 0
	global_store_dwordx4 v2, v[216:219], s[18:19] nt
	v_mov_b32_e32 v164, v200
	v_mbcnt_hi_u32_b32 v155, -1, v194
	v_and_b32_e32 v0, 64, v155
	v_mov_b32_e32 v154, 0x358637bd
	v_xor_b32_e32 v156, 32, v155
	v_add_u32_e32 v157, 64, v0
	v_mov_b32_e32 v158, 0xf149f2ca
	v_mov_b32_e32 v159, 0x7149f2ca
	v_mov_b32_e32 v160, 0x2080
	v_mov_b32_e32 v161, 0x461c4000
	v_mov_b32_e32 v162, 0xffffff80
	v_mov_b32_e32 v163, 0x63
	s_branch .Lp3_item_end
